# ssd_out unit: decay-scale load no longer waited alone, second half-tile's 8 y/z loads issued with the first; prompt attention unit start no longer waits for the q loads before its first barrier
# speedup vs baseline: 1.0146x; 1.0074x over previous
.LBB0_1079:
	v_mov_b32_e32 v139, v116
	s_mov_b32 s44, s88
	s_lshl_b32 s37, s44, 3
	v_lshrrev_b32_e32 v0, 2, v139
	v_and_or_b32 v6, v0, 7, s37
	s_lshl_b32 s46, s11, 3
	v_cmp_gt_i32_e64 s[2:3], 64, v6
	s_and_b32 s10, s11, 7
	s_andn2_b32 s46, s46, 63
	v_writelane_b32 v255, s2, 30
	s_lshl_b32 s4, s10, 11
	v_and_b32_e32 v7, 3, v139
	v_cndmask_b32_e64 v140, 0, v6, s[2:3]
	v_add_u32_e32 v137, s46, v140
	v_add_u32_e32 v118, s4, v137
	v_ashrrev_i32_e32 v119, 31, v118
	v_lshlrev_b64 v[0:1], 9, v[118:119]
	v_ashrrev_i32_e32 v141, 5, v139
	v_lshl_add_u64 v[0:1], s[38:39], 0, v[0:1]
	v_lshlrev_b32_e32 v2, 7, v7
	v_mov_b32_e32 v3, v96
	v_lshl_add_u64 v[0:1], v[0:1], 0, v[2:3]
	v_lshlrev_b32_e32 v2, 3, v141
	v_ashrrev_i32_e32 v3, 31, v2
	v_lshl_add_u64 v[0:1], v[2:3], 1, v[0:1]
	global_load_dwordx4 v[64:67], v[0:1], off
	global_load_dwordx4 v[68:71], v[0:1], off offset:32
	global_load_dwordx4 v[72:75], v[0:1], off offset:64
	global_load_dwordx4 v[76:79], v[0:1], off offset:96
	v_writelane_b32 v255, s3, 31
	v_writelane_b32 v255, s4, 32
	s_bfe_u32 s4, s11, 0x1c0001
	s_add_i32 s4, s4, 64
	s_lshl_b32 s2, s44, 6
	s_or_b32 s3, s46, 32
	s_lshr_b32 s4, s4, 6
	s_cmpk_lt_u32 s3, 0x7f0
	s_cselect_b32 s6, s4, 2
	s_cmpk_gt_i32 s46, 0xffdf
	s_cselect_b64 s[4:5], -1, 0
	v_add_u32_e32 v99, s2, v139
	s_and_b64 s[2:3], s[4:5], exec
	s_cselect_b32 s14, s6, 0
	s_lshl_b32 s15, s14, 1
	v_cmp_gt_i32_e32 vcc, s15, v99
	v_lshl_add_u32 v97, v99, 2, 0
	s_barrier
	s_and_saveexec_b64 s[6:7], vcc
	s_cbranch_execz .LBB0_1081
	v_mov_b32_e32 v0, s14
	v_cmp_le_i32_e32 vcc, s14, v99
	s_nop 1
	v_cndmask_b32_e32 v0, 0, v0, vcc
	v_sub_u32_e32 v0, v99, v0
	v_cndmask_b32_e64 v1, 0, 1, vcc
	v_lshl_or_b32 v0, v0, 4, v1
	ds_write_b32 v97, v0 offset:51264

.LBB0_1290:
	s_or_b64 exec, exec, s[4:5]
	v_readlane_b32 s2, v254, 53
	s_waitcnt lgkmcnt(0)
	s_barrier
	v_mov_b32_e32 v0, s2
	ds_read_b32 v0, v0
	s_mov_b64 s[4:5], -1
	s_waitcnt lgkmcnt(0)
	v_readfirstlane_b32 s2, v0
	s_cmpk_gt_i32 s2, 0xff
	s_cbranch_scc1 .LBB0_1285
	s_ashr_i32 s4, s2, 5
	s_and_b32 s3, s2, 31
	s_ashr_i32 s5, s4, 31
	s_lshl_b32 s2, s2, 2
	s_lshl_b32 s16, s3, 6
	s_lshl_b64 s[14:15], s[4:5], 7
	s_and_b32 s2, s2, 0x78
	s_add_u32 s3, s14, s88
	s_addc_u32 s14, s15, 0
	s_add_u32 s2, s3, s2
	s_addc_u32 s3, s14, 0
	s_lshl_b64 s[2:3], s[2:3], 14
	v_lshl_add_u64 v[4:5], v[86:87], 0, s[2:3]
	v_mov_b32_e32 v103, v96
	v_mov_b32_e32 v105, v96
	s_lshl_b64 s[4:5], s[4:5], 11
	v_lshl_add_u64 v[80:81], v[4:5], 0, v[102:103]
	v_lshl_add_u64 v[82:83], v[4:5], 0, v[104:105]
	s_or_b32 s4, s4, s16
	global_load_dwordx4 v[0:3], v[80:81], off
	global_load_dwordx4 v[4:7], v[82:83], off
	s_lshl_b64 s[14:15], s[4:5], 9
	v_lshl_add_u64 v[12:13], v[88:89], 0, s[14:15]
	v_mov_b32_e32 v107, v96
	v_mov_b32_e32 v109, v96
	v_lshl_add_u64 v[110:111], v[12:13], 0, v[106:107]
	v_lshl_add_u64 v[112:113], v[12:13], 0, v[108:109]
	global_load_dwordx4 v[8:11], v[110:111], off
	global_load_dwordx4 v[12:15], v[112:113], off
	global_load_dwordx4 v[64:67], v[80:81], off offset:32
	global_load_dwordx4 v[68:71], v[82:83], off offset:32
	global_load_dwordx4 v[72:75], v[110:111], off offset:32
	global_load_dwordx4 v[76:79], v[112:113], off offset:32
	s_waitcnt vmcnt(5)
	v_mfma_f32_32x32x16_bf16 v[48:63], v[0:3], v[8:11], 0
	v_mfma_f32_32x32x16_bf16 v[32:47], v[4:7], v[8:11], 0
	s_waitcnt vmcnt(4)
	v_mfma_f32_32x32x16_bf16 v[16:31], v[0:3], v[12:15], 0
	v_mfma_f32_32x32x16_bf16 v[0:15], v[4:7], v[12:15], 0
	s_waitcnt vmcnt(1)
	v_mfma_f32_32x32x16_bf16 v[48:63], v[64:67], v[72:75], v[48:63]
	v_mfma_f32_32x32x16_bf16 v[32:47], v[68:71], v[72:75], v[32:47]
	s_waitcnt vmcnt(0)
	v_mfma_f32_32x32x16_bf16 v[16:31], v[64:67], v[76:79], v[16:31]
	v_mfma_f32_32x32x16_bf16 v[0:15], v[68:71], v[76:79], v[0:15]
	global_load_dwordx4 v[64:67], v[80:81], off offset:64
	global_load_dwordx4 v[68:71], v[82:83], off offset:64
	global_load_dwordx4 v[72:75], v[110:111], off offset:64
	global_load_dwordx4 v[76:79], v[112:113], off offset:64
	s_waitcnt vmcnt(1)
	v_mfma_f32_32x32x16_bf16 v[48:63], v[64:67], v[72:75], v[48:63]
	v_mfma_f32_32x32x16_bf16 v[32:47], v[68:71], v[72:75], v[32:47]
	s_waitcnt vmcnt(0)
	v_mfma_f32_32x32x16_bf16 v[16:31], v[64:67], v[76:79], v[16:31]
	v_mfma_f32_32x32x16_bf16 v[0:15], v[68:71], v[76:79], v[0:15]
	global_load_dwordx4 v[64:67], v[80:81], off offset:96
	global_load_dwordx4 v[68:71], v[82:83], off offset:96
	global_load_dwordx4 v[72:75], v[110:111], off offset:96
	global_load_dwordx4 v[76:79], v[112:113], off offset:96
	s_waitcnt vmcnt(1)
	v_mfma_f32_32x32x16_bf16 v[48:63], v[64:67], v[72:75], v[48:63]
	v_mfma_f32_32x32x16_bf16 v[32:47], v[68:71], v[72:75], v[32:47]
	s_waitcnt vmcnt(0)
	v_mfma_f32_32x32x16_bf16 v[16:31], v[64:67], v[76:79], v[16:31]
	v_mfma_f32_32x32x16_bf16 v[0:15], v[68:71], v[76:79], v[0:15]
	global_load_dwordx4 v[64:67], v[80:81], off offset:128
	global_load_dwordx4 v[68:71], v[82:83], off offset:128
	global_load_dwordx4 v[72:75], v[110:111], off offset:128
	global_load_dwordx4 v[76:79], v[112:113], off offset:128
	s_waitcnt vmcnt(1)
	v_mfma_f32_32x32x16_bf16 v[48:63], v[64:67], v[72:75], v[48:63]
	v_mfma_f32_32x32x16_bf16 v[32:47], v[68:71], v[72:75], v[32:47]
	s_waitcnt vmcnt(0)
	v_mfma_f32_32x32x16_bf16 v[16:31], v[64:67], v[76:79], v[16:31]
	v_mfma_f32_32x32x16_bf16 v[0:15], v[68:71], v[76:79], v[0:15]
	global_load_dwordx4 v[64:67], v[80:81], off offset:160
	global_load_dwordx4 v[68:71], v[82:83], off offset:160
	global_load_dwordx4 v[72:75], v[110:111], off offset:160
	global_load_dwordx4 v[76:79], v[112:113], off offset:160
	s_waitcnt vmcnt(1)
	v_mfma_f32_32x32x16_bf16 v[48:63], v[64:67], v[72:75], v[48:63]
	v_mfma_f32_32x32x16_bf16 v[32:47], v[68:71], v[72:75], v[32:47]
	s_waitcnt vmcnt(0)
	v_mfma_f32_32x32x16_bf16 v[16:31], v[64:67], v[76:79], v[16:31]
	v_mfma_f32_32x32x16_bf16 v[0:15], v[68:71], v[76:79], v[0:15]
	global_load_dwordx4 v[64:67], v[80:81], off offset:192
	global_load_dwordx4 v[68:71], v[82:83], off offset:192
	global_load_dwordx4 v[72:75], v[110:111], off offset:192
	global_load_dwordx4 v[76:79], v[112:113], off offset:192
	s_waitcnt vmcnt(1)
	v_mfma_f32_32x32x16_bf16 v[48:63], v[64:67], v[72:75], v[48:63]
	v_mfma_f32_32x32x16_bf16 v[32:47], v[68:71], v[72:75], v[32:47]
	s_waitcnt vmcnt(0)
	v_mfma_f32_32x32x16_bf16 v[16:31], v[64:67], v[76:79], v[16:31]
	v_mfma_f32_32x32x16_bf16 v[0:15], v[68:71], v[76:79], v[0:15]
	global_load_dwordx4 v[64:67], v[80:81], off offset:224
	global_load_dwordx4 v[68:71], v[82:83], off offset:224
	global_load_dwordx4 v[72:75], v[110:111], off offset:224
	global_load_dwordx4 v[76:79], v[112:113], off offset:224
	s_barrier
	s_waitcnt vmcnt(1)
	v_mfma_f32_32x32x16_bf16 v[32:47], v[68:71], v[72:75], v[32:47]
	s_waitcnt vmcnt(0)
	v_mfma_f32_32x32x16_bf16 v[0:15], v[68:71], v[76:79], v[0:15]
	v_mov_b32_e32 v69, s5
	v_or_b32_e32 v68, s4, v84
	v_lshlrev_b64 v[110:111], 11, v[68:69]
	v_mad_u64_u32 v[130:131], s[2:3], v68, s42, v[98:99]
	v_lshl_add_u64 v[128:129], v[94:95], 0, v[110:111]
	v_mfma_f32_32x32x16_bf16 v[48:63], v[64:67], v[72:75], v[48:63]
	v_mfma_f32_32x32x16_bf16 v[16:31], v[64:67], v[76:79], v[16:31]
	v_lshlrev_b64 v[64:65], 5, v[68:69]
	v_lshl_add_u64 v[64:65], s[8:9], 0, v[64:65]
	global_load_dword v142, v[64:65], off
	v_mov_b32_e32 v68, 0x2800
	v_mad_i32_i24 v131, s5, v68, v131
	global_load_dwordx4 v[64:67], v[128:129], off
	global_load_dwordx4 v[112:115], v[130:131], off
	global_load_dwordx4 v[120:123], v[128:129], off offset:32
	global_load_dwordx4 v[132:135], v[130:131], off offset:32
	global_load_dwordx4 v[80:83], v[128:129], off offset:64
	global_load_dwordx4 v[76:79], v[130:131], off offset:64
	global_load_dwordx4 v[72:75], v[128:129], off offset:96
	global_load_dwordx4 v[68:71], v[130:131], off offset:96
	global_load_dwordx4 v[186:189], v[128:129], off offset:128
	global_load_dwordx4 v[190:193], v[130:131], off offset:128
	global_load_dwordx4 v[194:197], v[128:129], off offset:160
	global_load_dwordx4 v[198:201], v[130:131], off offset:160
	global_load_dwordx4 v[202:205], v[128:129], off offset:192
	global_load_dwordx4 v[206:209], v[130:131], off offset:192
	global_load_dwordx4 v[210:213], v[128:129], off offset:224
	global_load_dwordx4 v[214:217], v[130:131], off offset:224
	s_waitcnt vmcnt(16)
	v_exp_f32_e32 v124, v142
	s_waitcnt vmcnt(14)
	v_mul_f32_e32 v103, 0xbfb8aa3b, v112
	v_fma_f32 v105, v112, s43, -v103
	v_rndne_f32_e32 v107, v103
	v_fmac_f32_e32 v105, 0xb2a5705f, v112
	v_sub_f32_e32 v103, v103, v107
	v_add_f32_e32 v103, v103, v105
	v_exp_f32_e32 v103, v103
	v_cvt_i32_f32_e32 v105, v107
	v_cmp_nlt_f32_e32 vcc, s34, v112
	v_pk_fma_f32 v[48:49], v[48:49], v[124:125], v[64:65] op_sel_hi:[1,0,1]
	v_pk_fma_f32 v[50:51], v[50:51], v[124:125], v[66:67] op_sel_hi:[1,0,1]
	v_ldexp_f32 v103, v103, v105
	v_cndmask_b32_e32 v103, 0, v103, vcc
	v_cmp_ngt_f32_e32 vcc, s35, v112
	s_waitcnt vmcnt(13)
	v_pk_fma_f32 v[52:53], v[52:53], v[124:125], v[120:121] op_sel_hi:[1,0,1]
	v_cndmask_b32_e32 v116, v179, v103, vcc
	v_mul_f32_e32 v103, 0xbfb8aa3b, v113
	v_fma_f32 v105, v113, s43, -v103
	v_rndne_f32_e32 v107, v103
	v_fmac_f32_e32 v105, 0xb2a5705f, v113
	v_sub_f32_e32 v103, v103, v107
	v_add_f32_e32 v103, v103, v105
	v_exp_f32_e32 v103, v103
	v_cvt_i32_f32_e32 v105, v107
	v_cmp_nlt_f32_e32 vcc, s34, v113
	v_ldexp_f32 v103, v103, v105
	s_nop 0
	v_cndmask_b32_e32 v103, 0, v103, vcc
	v_cmp_ngt_f32_e32 vcc, s35, v113
	s_nop 1
	v_cndmask_b32_e32 v117, v179, v103, vcc
	v_pk_add_f32 v[64:65], v[116:117], 1.0 op_sel_hi:[1,0]
	s_nop 0
	v_div_scale_f32 v103, s[2:3], v65, v65, v113
	v_rcp_f32_e32 v105, v103
	s_nop 0
	v_fma_f32 v107, -v103, v105, 1.0
	v_fmac_f32_e32 v105, v107, v105
	v_div_scale_f32 v107, vcc, v113, v65, v113
	v_mul_f32_e32 v109, v107, v105
	v_fma_f32 v116, -v103, v109, v107
	v_fmac_f32_e32 v109, v116, v105
	v_fma_f32 v103, -v103, v109, v107
	v_div_fmas_f32 v103, v103, v105, v109
	v_div_fixup_f32 v65, v103, v65, v113
	v_div_scale_f32 v103, s[2:3], v64, v64, v112
	v_rcp_f32_e32 v105, v103
	s_nop 0
	v_fma_f32 v107, -v103, v105, 1.0
	v_fmac_f32_e32 v105, v107, v105
	v_div_scale_f32 v107, vcc, v112, v64, v112
	v_mul_f32_e32 v109, v107, v105
	v_fma_f32 v113, -v103, v109, v107
	v_fmac_f32_e32 v109, v113, v105
	v_fma_f32 v103, -v103, v109, v107
	v_div_fmas_f32 v103, v103, v105, v109
	v_div_fixup_f32 v64, v103, v64, v112
	v_pk_mul_f32 v[116:117], v[48:49], v[64:65]
	v_mul_f32_e32 v64, 0xbfb8aa3b, v114
	v_fma_f32 v65, v114, s43, -v64
	v_rndne_f32_e32 v103, v64
	v_fmac_f32_e32 v65, 0xb2a5705f, v114
	v_sub_f32_e32 v64, v64, v103
	v_add_f32_e32 v64, v64, v65
	v_exp_f32_e32 v64, v64
	v_cvt_i32_f32_e32 v65, v103
	v_cmp_nlt_f32_e32 vcc, s34, v114
	v_mul_f32_e32 v48, v117, v117
	v_pk_fma_f32 v[48:49], v[116:117], v[116:117], v[48:49] op_sel_hi:[1,1,0]
	v_ldexp_f32 v64, v64, v65
	v_mul_f32_e32 v65, 0xbfb8aa3b, v115
	v_fma_f32 v103, v115, s43, -v65
	v_rndne_f32_e32 v105, v65
	v_fmac_f32_e32 v103, 0xb2a5705f, v115
	v_sub_f32_e32 v65, v65, v105
	v_add_f32_e32 v65, v65, v103
	v_exp_f32_e32 v65, v65
	v_cvt_i32_f32_e32 v103, v105
	v_cndmask_b32_e32 v64, 0, v64, vcc
	v_cmp_ngt_f32_e32 vcc, s35, v114
	v_ldexp_f32 v65, v65, v103
	s_nop 0
	v_cndmask_b32_e32 v64, v179, v64, vcc
	v_cmp_nlt_f32_e32 vcc, s34, v115
	s_nop 1
	v_cndmask_b32_e32 v65, 0, v65, vcc
	v_cmp_ngt_f32_e32 vcc, s35, v115
	s_nop 1
	v_cndmask_b32_e32 v65, v179, v65, vcc
	v_pk_add_f32 v[64:65], v[64:65], 1.0 op_sel_hi:[1,0]
	s_nop 0
	v_div_scale_f32 v66, s[2:3], v65, v65, v115
	v_rcp_f32_e32 v67, v66
	s_nop 0
	v_fma_f32 v103, -v66, v67, 1.0
	v_fmac_f32_e32 v67, v103, v67
	v_div_scale_f32 v103, vcc, v115, v65, v115
	v_mul_f32_e32 v105, v103, v67
	v_fma_f32 v107, -v66, v105, v103
	v_fmac_f32_e32 v105, v107, v67
	v_fma_f32 v66, -v66, v105, v103
	v_div_fmas_f32 v66, v66, v67, v105
	v_div_fixup_f32 v65, v66, v65, v115
	v_div_scale_f32 v66, s[2:3], v64, v64, v114
	v_rcp_f32_e32 v67, v66
	s_nop 0
	v_fma_f32 v103, -v66, v67, 1.0
	v_fmac_f32_e32 v67, v103, v67
	v_div_scale_f32 v103, vcc, v114, v64, v114
	v_mul_f32_e32 v105, v103, v67
	v_fma_f32 v107, -v66, v105, v103
	v_fmac_f32_e32 v105, v107, v67
	v_fma_f32 v66, -v66, v105, v103
	v_div_fmas_f32 v66, v66, v67, v105
	v_div_fixup_f32 v64, v66, v64, v114
	v_pk_mul_f32 v[118:119], v[50:51], v[64:65]
	s_waitcnt vmcnt(12)
	v_cmp_nlt_f32_e32 vcc, s34, v132
	v_pk_fma_f32 v[48:49], v[118:119], v[118:119], v[48:49]
	v_mul_f32_e32 v50, v119, v119
	v_pk_add_f32 v[48:49], v[50:51], v[48:49] op_sel_hi:[0,1]
	v_mul_f32_e32 v50, 0xbfb8aa3b, v132
	v_fma_f32 v51, v132, s43, -v50
	v_rndne_f32_e32 v64, v50
	v_fmac_f32_e32 v51, 0xb2a5705f, v132
	v_sub_f32_e32 v50, v50, v64
	v_add_f32_e32 v50, v50, v51
	v_exp_f32_e32 v50, v50
	v_cvt_i32_f32_e32 v51, v64
	v_ldexp_f32 v50, v50, v51
	v_mul_f32_e32 v51, 0xbfb8aa3b, v133
	v_fma_f32 v64, v133, s43, -v51
	v_rndne_f32_e32 v65, v51
	v_fmac_f32_e32 v64, 0xb2a5705f, v133
	v_sub_f32_e32 v51, v51, v65
	v_add_f32_e32 v51, v51, v64
	v_exp_f32_e32 v51, v51
	v_cvt_i32_f32_e32 v64, v65
	v_cndmask_b32_e32 v50, 0, v50, vcc
	v_cmp_ngt_f32_e32 vcc, s35, v132
	v_ldexp_f32 v51, v51, v64
	s_nop 0
	v_cndmask_b32_e32 v50, v179, v50, vcc
	v_cmp_nlt_f32_e32 vcc, s34, v133
	s_nop 1
	v_cndmask_b32_e32 v51, 0, v51, vcc
	v_cmp_ngt_f32_e32 vcc, s35, v133
	s_nop 1
	v_cndmask_b32_e32 v51, v179, v51, vcc
	v_pk_add_f32 v[50:51], v[50:51], 1.0 op_sel_hi:[1,0]
	s_nop 0
	v_div_scale_f32 v64, s[2:3], v51, v51, v133
	v_rcp_f32_e32 v65, v64
	s_nop 0
	v_fma_f32 v66, -v64, v65, 1.0
	v_fmac_f32_e32 v65, v66, v65
	v_div_scale_f32 v66, vcc, v133, v51, v133
	v_mul_f32_e32 v67, v66, v65
	v_fma_f32 v103, -v64, v67, v66
	v_fmac_f32_e32 v67, v103, v65
	v_fma_f32 v64, -v64, v67, v66
	v_div_fmas_f32 v64, v64, v65, v67
	v_div_fixup_f32 v51, v64, v51, v133
	v_div_scale_f32 v64, s[2:3], v50, v50, v132
	v_rcp_f32_e32 v65, v64
	s_nop 0
	v_fma_f32 v66, -v64, v65, 1.0
	v_fmac_f32_e32 v65, v66, v65
	v_div_scale_f32 v66, vcc, v132, v50, v132
	v_mul_f32_e32 v67, v66, v65
	v_fma_f32 v103, -v64, v67, v66
	v_fmac_f32_e32 v67, v103, v65
	v_fma_f32 v64, -v64, v67, v66
	v_div_fmas_f32 v64, v64, v65, v67
	v_div_fixup_f32 v50, v64, v50, v132
	v_pk_mul_f32 v[112:113], v[52:53], v[50:51]
	v_cmp_nlt_f32_e32 vcc, s34, v134
	v_pk_fma_f32 v[48:49], v[112:113], v[112:113], v[48:49]
	v_mul_f32_e32 v50, v113, v113
	v_pk_add_f32 v[48:49], v[50:51], v[48:49] op_sel_hi:[0,1]
	v_mul_f32_e32 v50, 0xbfb8aa3b, v134
	v_fma_f32 v51, v134, s43, -v50
	v_rndne_f32_e32 v52, v50
	v_fmac_f32_e32 v51, 0xb2a5705f, v134
	v_sub_f32_e32 v50, v50, v52
	v_add_f32_e32 v50, v50, v51
	v_exp_f32_e32 v50, v50
	v_cvt_i32_f32_e32 v51, v52
	v_ldexp_f32 v50, v50, v51
	v_mul_f32_e32 v51, 0xbfb8aa3b, v135
	v_fma_f32 v52, v135, s43, -v51
	v_rndne_f32_e32 v53, v51
	v_fmac_f32_e32 v52, 0xb2a5705f, v135
	v_sub_f32_e32 v51, v51, v53
	v_add_f32_e32 v51, v51, v52
	v_exp_f32_e32 v51, v51
	v_cvt_i32_f32_e32 v52, v53
	v_cndmask_b32_e32 v50, 0, v50, vcc
	v_cmp_ngt_f32_e32 vcc, s35, v134
	v_ldexp_f32 v51, v51, v52
	s_nop 0
	v_cndmask_b32_e32 v50, v179, v50, vcc
	v_cmp_nlt_f32_e32 vcc, s34, v135
	v_pk_fma_f32 v[52:53], v[54:55], v[124:125], v[122:123] op_sel_hi:[1,0,1]
	s_nop 0
	v_cndmask_b32_e32 v51, 0, v51, vcc
	v_cmp_ngt_f32_e32 vcc, s35, v135
	s_nop 1
	v_cndmask_b32_e32 v51, v179, v51, vcc
	v_pk_add_f32 v[50:51], v[50:51], 1.0 op_sel_hi:[1,0]
	s_nop 0
	v_div_scale_f32 v54, s[2:3], v51, v51, v135
	v_rcp_f32_e32 v55, v54
	s_nop 0
	v_fma_f32 v64, -v54, v55, 1.0
	v_fmac_f32_e32 v55, v64, v55
	v_div_scale_f32 v64, vcc, v135, v51, v135
	v_mul_f32_e32 v65, v64, v55
	v_fma_f32 v66, -v54, v65, v64
	v_fmac_f32_e32 v65, v66, v55
	v_fma_f32 v54, -v54, v65, v64
	v_div_fmas_f32 v54, v54, v55, v65
	v_div_fixup_f32 v51, v54, v51, v135
	v_div_scale_f32 v54, s[2:3], v50, v50, v134
	v_rcp_f32_e32 v55, v54
	s_nop 0
	v_fma_f32 v64, -v54, v55, 1.0
	v_fmac_f32_e32 v55, v64, v55
	v_div_scale_f32 v64, vcc, v134, v50, v134
	v_mul_f32_e32 v65, v64, v55
	v_fma_f32 v66, -v54, v65, v64
	v_fmac_f32_e32 v65, v66, v55
	v_fma_f32 v54, -v54, v65, v64
	v_div_fmas_f32 v54, v54, v55, v65
	v_div_fixup_f32 v50, v54, v50, v134
	v_pk_mul_f32 v[114:115], v[52:53], v[50:51]
	s_waitcnt vmcnt(10)
	v_cmp_nlt_f32_e32 vcc, s34, v76
	v_pk_fma_f32 v[48:49], v[114:115], v[114:115], v[48:49]
	v_mul_f32_e32 v50, v115, v115
	v_pk_add_f32 v[48:49], v[50:51], v[48:49] op_sel_hi:[0,1]
	v_mul_f32_e32 v50, 0xbfb8aa3b, v76
	v_fma_f32 v51, v76, s43, -v50
	v_rndne_f32_e32 v52, v50
	v_fmac_f32_e32 v51, 0xb2a5705f, v76
	v_sub_f32_e32 v50, v50, v52
	v_add_f32_e32 v50, v50, v51
	v_exp_f32_e32 v50, v50
	v_cvt_i32_f32_e32 v51, v52
	v_ldexp_f32 v50, v50, v51
	v_mul_f32_e32 v51, 0xbfb8aa3b, v77
	v_fma_f32 v52, v77, s43, -v51
	v_rndne_f32_e32 v53, v51
	v_fmac_f32_e32 v52, 0xb2a5705f, v77
	v_sub_f32_e32 v51, v51, v53
	v_add_f32_e32 v51, v51, v52
	v_exp_f32_e32 v51, v51
	v_cvt_i32_f32_e32 v52, v53
	v_cndmask_b32_e32 v50, 0, v50, vcc
	v_cmp_ngt_f32_e32 vcc, s35, v76
	v_ldexp_f32 v51, v51, v52
	s_nop 0
	v_cndmask_b32_e32 v50, v179, v50, vcc
	v_cmp_nlt_f32_e32 vcc, s34, v77
	v_pk_fma_f32 v[52:53], v[56:57], v[124:125], v[80:81] op_sel_hi:[1,0,1]
	s_nop 0
	v_cndmask_b32_e32 v51, 0, v51, vcc
	v_cmp_ngt_f32_e32 vcc, s35, v77
	s_nop 1
	v_cndmask_b32_e32 v51, v179, v51, vcc
	v_pk_add_f32 v[50:51], v[50:51], 1.0 op_sel_hi:[1,0]
	s_nop 0
	v_div_scale_f32 v54, s[2:3], v51, v51, v77
	v_rcp_f32_e32 v55, v54
	s_nop 0
	v_fma_f32 v56, -v54, v55, 1.0
	v_fmac_f32_e32 v55, v56, v55
	v_div_scale_f32 v56, vcc, v77, v51, v77
	v_mul_f32_e32 v57, v56, v55
	v_fma_f32 v64, -v54, v57, v56
	v_fmac_f32_e32 v57, v64, v55
	v_fma_f32 v54, -v54, v57, v56
	v_div_fmas_f32 v54, v54, v55, v57
	v_div_fixup_f32 v51, v54, v51, v77
	v_div_scale_f32 v54, s[2:3], v50, v50, v76
	v_rcp_f32_e32 v55, v54
	s_nop 0
	v_fma_f32 v56, -v54, v55, 1.0
	v_fmac_f32_e32 v55, v56, v55
	v_div_scale_f32 v56, vcc, v76, v50, v76
	v_mul_f32_e32 v57, v56, v55
	v_fma_f32 v64, -v54, v57, v56
	v_fmac_f32_e32 v57, v64, v55
	v_fma_f32 v54, -v54, v57, v56
	v_div_fmas_f32 v54, v54, v55, v57
	v_div_fixup_f32 v50, v54, v50, v76
	v_pk_mul_f32 v[80:81], v[52:53], v[50:51]
	v_cmp_nlt_f32_e32 vcc, s34, v78
	v_pk_fma_f32 v[48:49], v[80:81], v[80:81], v[48:49]
	v_mul_f32_e32 v50, v81, v81
	v_pk_add_f32 v[48:49], v[50:51], v[48:49] op_sel_hi:[0,1]
	v_mul_f32_e32 v50, 0xbfb8aa3b, v78
	v_fma_f32 v51, v78, s43, -v50
	v_rndne_f32_e32 v52, v50
	v_fmac_f32_e32 v51, 0xb2a5705f, v78
	v_sub_f32_e32 v50, v50, v52
	v_add_f32_e32 v50, v50, v51
	v_exp_f32_e32 v50, v50
	v_cvt_i32_f32_e32 v51, v52
	v_ldexp_f32 v50, v50, v51
	v_mul_f32_e32 v51, 0xbfb8aa3b, v79
	v_fma_f32 v52, v79, s43, -v51
	v_rndne_f32_e32 v53, v51
	v_fmac_f32_e32 v52, 0xb2a5705f, v79
	v_sub_f32_e32 v51, v51, v53
	v_add_f32_e32 v51, v51, v52
	v_exp_f32_e32 v51, v51
	v_cvt_i32_f32_e32 v52, v53
	v_cndmask_b32_e32 v50, 0, v50, vcc
	v_cmp_ngt_f32_e32 vcc, s35, v78
	v_ldexp_f32 v51, v51, v52
	s_nop 0
	v_cndmask_b32_e32 v50, v179, v50, vcc
	v_cmp_nlt_f32_e32 vcc, s34, v79
	v_pk_fma_f32 v[52:53], v[58:59], v[124:125], v[82:83] op_sel_hi:[1,0,1]
	s_nop 0
	v_cndmask_b32_e32 v51, 0, v51, vcc
	v_cmp_ngt_f32_e32 vcc, s35, v79
	s_nop 1
	v_cndmask_b32_e32 v51, v179, v51, vcc
	v_pk_add_f32 v[50:51], v[50:51], 1.0 op_sel_hi:[1,0]
	s_nop 0
	v_div_scale_f32 v54, s[2:3], v51, v51, v79
	v_rcp_f32_e32 v55, v54
	s_nop 0
	v_fma_f32 v56, -v54, v55, 1.0
	v_fmac_f32_e32 v55, v56, v55
	v_div_scale_f32 v56, vcc, v79, v51, v79
	v_mul_f32_e32 v57, v56, v55
	v_fma_f32 v58, -v54, v57, v56
	v_fmac_f32_e32 v57, v58, v55
	v_fma_f32 v54, -v54, v57, v56
	v_div_fmas_f32 v54, v54, v55, v57
	v_div_fixup_f32 v51, v54, v51, v79
	v_div_scale_f32 v54, s[2:3], v50, v50, v78
	v_rcp_f32_e32 v55, v54
	s_nop 0
	v_fma_f32 v56, -v54, v55, 1.0
	v_fmac_f32_e32 v55, v56, v55
	v_div_scale_f32 v56, vcc, v78, v50, v78
	v_mul_f32_e32 v57, v56, v55
	v_fma_f32 v58, -v54, v57, v56
	v_fmac_f32_e32 v57, v58, v55
	v_fma_f32 v54, -v54, v57, v56
	v_div_fmas_f32 v54, v54, v55, v57
	v_div_fixup_f32 v50, v54, v50, v78
	v_pk_mul_f32 v[82:83], v[52:53], v[50:51]
	s_waitcnt vmcnt(8)
	v_cmp_nlt_f32_e32 vcc, s34, v68
	v_pk_fma_f32 v[48:49], v[82:83], v[82:83], v[48:49]
	v_mul_f32_e32 v50, v83, v83
	v_pk_add_f32 v[48:49], v[50:51], v[48:49] op_sel_hi:[0,1]
	v_mul_f32_e32 v50, 0xbfb8aa3b, v68
	v_fma_f32 v51, v68, s43, -v50
	v_rndne_f32_e32 v52, v50
	v_fmac_f32_e32 v51, 0xb2a5705f, v68
	v_sub_f32_e32 v50, v50, v52
	v_add_f32_e32 v50, v50, v51
	v_exp_f32_e32 v50, v50
	v_cvt_i32_f32_e32 v51, v52
	v_ldexp_f32 v50, v50, v51
	v_mul_f32_e32 v51, 0xbfb8aa3b, v69
	v_fma_f32 v52, v69, s43, -v51
	v_rndne_f32_e32 v53, v51
	v_fmac_f32_e32 v52, 0xb2a5705f, v69
	v_sub_f32_e32 v51, v51, v53
	v_add_f32_e32 v51, v51, v52
	v_exp_f32_e32 v51, v51
	v_cvt_i32_f32_e32 v52, v53
	v_cndmask_b32_e32 v50, 0, v50, vcc
	v_cmp_ngt_f32_e32 vcc, s35, v68
	v_ldexp_f32 v51, v51, v52
	s_nop 0
	v_cndmask_b32_e32 v50, v179, v50, vcc
	v_cmp_nlt_f32_e32 vcc, s34, v69
	v_pk_fma_f32 v[52:53], v[60:61], v[124:125], v[72:73] op_sel_hi:[1,0,1]
	s_nop 0
	v_cndmask_b32_e32 v51, 0, v51, vcc
	v_cmp_ngt_f32_e32 vcc, s35, v69
	s_nop 1
	v_cndmask_b32_e32 v51, v179, v51, vcc
	v_pk_add_f32 v[50:51], v[50:51], 1.0 op_sel_hi:[1,0]
	s_nop 0
	v_div_scale_f32 v54, s[2:3], v51, v51, v69
	v_rcp_f32_e32 v55, v54
	s_nop 0
	v_fma_f32 v56, -v54, v55, 1.0
	v_fmac_f32_e32 v55, v56, v55
	v_div_scale_f32 v56, vcc, v69, v51, v69
	v_mul_f32_e32 v57, v56, v55
	v_fma_f32 v58, -v54, v57, v56
	v_fmac_f32_e32 v57, v58, v55
	v_fma_f32 v54, -v54, v57, v56
	v_div_fmas_f32 v54, v54, v55, v57
	v_div_fixup_f32 v51, v54, v51, v69
	v_div_scale_f32 v54, s[2:3], v50, v50, v68
	v_rcp_f32_e32 v55, v54
	s_nop 0
	v_fma_f32 v56, -v54, v55, 1.0
	v_fmac_f32_e32 v55, v56, v55
	v_div_scale_f32 v56, vcc, v68, v50, v68
	v_mul_f32_e32 v57, v56, v55
	v_fma_f32 v58, -v54, v57, v56
	v_fmac_f32_e32 v57, v58, v55
	v_fma_f32 v54, -v54, v57, v56
	v_div_fmas_f32 v54, v54, v55, v57
	v_div_fixup_f32 v50, v54, v50, v68
	v_pk_mul_f32 v[120:121], v[52:53], v[50:51]
	v_cmp_nlt_f32_e32 vcc, s34, v70
	v_pk_fma_f32 v[48:49], v[120:121], v[120:121], v[48:49]
	v_mul_f32_e32 v50, v121, v121
	v_pk_add_f32 v[48:49], v[50:51], v[48:49] op_sel_hi:[0,1]
	v_mul_f32_e32 v50, 0xbfb8aa3b, v70
	v_fma_f32 v51, v70, s43, -v50
	v_rndne_f32_e32 v52, v50
	v_fmac_f32_e32 v51, 0xb2a5705f, v70
	v_sub_f32_e32 v50, v50, v52
	v_add_f32_e32 v50, v50, v51
	v_exp_f32_e32 v50, v50
	v_cvt_i32_f32_e32 v51, v52
	v_ldexp_f32 v50, v50, v51
	v_mul_f32_e32 v51, 0xbfb8aa3b, v71
	v_fma_f32 v52, v71, s43, -v51
	v_rndne_f32_e32 v53, v51
	v_fmac_f32_e32 v52, 0xb2a5705f, v71
	v_sub_f32_e32 v51, v51, v53
	v_add_f32_e32 v51, v51, v52
	v_exp_f32_e32 v51, v51
	v_cvt_i32_f32_e32 v52, v53
	v_cndmask_b32_e32 v50, 0, v50, vcc
	v_cmp_ngt_f32_e32 vcc, s35, v70
	v_ldexp_f32 v51, v51, v52
	s_nop 0
	v_cndmask_b32_e32 v50, v179, v50, vcc
	v_cmp_nlt_f32_e32 vcc, s34, v71
	v_pk_fma_f32 v[52:53], v[62:63], v[124:125], v[74:75] op_sel_hi:[1,0,1]
	s_nop 0
	v_cndmask_b32_e32 v51, 0, v51, vcc
	v_cmp_ngt_f32_e32 vcc, s35, v71
	s_nop 1
	v_cndmask_b32_e32 v51, v179, v51, vcc
	v_pk_add_f32 v[50:51], v[50:51], 1.0 op_sel_hi:[1,0]
	s_nop 0
	v_div_scale_f32 v54, s[2:3], v51, v51, v71
	v_rcp_f32_e32 v55, v54
	s_nop 0
	v_fma_f32 v56, -v54, v55, 1.0
	v_fmac_f32_e32 v55, v56, v55
	v_div_scale_f32 v56, vcc, v71, v51, v71
	v_mul_f32_e32 v57, v56, v55
	v_fma_f32 v58, -v54, v57, v56
	v_fmac_f32_e32 v57, v58, v55
	v_fma_f32 v54, -v54, v57, v56
	v_div_fmas_f32 v54, v54, v55, v57
	v_div_fixup_f32 v51, v54, v51, v71
	v_div_scale_f32 v54, s[2:3], v50, v50, v70
	v_rcp_f32_e32 v55, v54
	s_nop 0
	v_fma_f32 v56, -v54, v55, 1.0
	v_fmac_f32_e32 v55, v56, v55
	v_div_scale_f32 v56, vcc, v70, v50, v70
	v_mul_f32_e32 v57, v56, v55
	v_fma_f32 v58, -v54, v57, v56
	v_fmac_f32_e32 v57, v58, v55
	v_fma_f32 v54, -v54, v57, v56
	v_div_fmas_f32 v54, v54, v55, v57
	v_div_fixup_f32 v50, v54, v50, v70
	v_pk_mul_f32 v[122:123], v[52:53], v[50:51]
	s_nop 0
	v_pk_fma_f32 v[48:49], v[122:123], v[122:123], v[48:49]
	v_mul_f32_e32 v50, v123, v123
	v_pk_add_f32 v[126:127], v[50:51], v[48:49] op_sel_hi:[0,1]
	s_waitcnt vmcnt(7)
	v_pk_fma_f32 v[32:33], v[32:33], v[124:125], v[186:187] op_sel_hi:[1,0,1]
	s_waitcnt vmcnt(6)
	v_mul_f32_e32 v103, 0xbfb8aa3b, v190
	v_fma_f32 v105, v190, s43, -v103
	v_rndne_f32_e32 v107, v103
	v_fmac_f32_e32 v105, 0xb2a5705f, v190
	v_sub_f32_e32 v103, v103, v107
	v_add_f32_e32 v103, v103, v105
	v_exp_f32_e32 v103, v103
	v_cvt_i32_f32_e32 v105, v107
	v_cmp_nlt_f32_e32 vcc, s34, v190
	v_ldexp_f32 v103, v103, v105
	s_nop 0
	v_cndmask_b32_e32 v103, 0, v103, vcc
	v_cmp_ngt_f32_e32 vcc, s35, v190
	s_nop 1
	v_cndmask_b32_e32 v128, v179, v103, vcc
	v_mul_f32_e32 v103, 0xbfb8aa3b, v191
	v_fma_f32 v105, v191, s43, -v103
	v_rndne_f32_e32 v107, v103
	v_fmac_f32_e32 v105, 0xb2a5705f, v191
	v_sub_f32_e32 v103, v103, v107
	v_add_f32_e32 v103, v103, v105
	v_exp_f32_e32 v103, v103
	v_cvt_i32_f32_e32 v105, v107
	v_cmp_nlt_f32_e32 vcc, s34, v191
	v_ldexp_f32 v103, v103, v105
	s_nop 0
	v_cndmask_b32_e32 v103, 0, v103, vcc
	v_cmp_ngt_f32_e32 vcc, s35, v191
	s_nop 1
	v_cndmask_b32_e32 v129, v179, v103, vcc
	v_pk_add_f32 v[68:69], v[128:129], 1.0 op_sel_hi:[1,0]
	s_nop 0
	v_div_scale_f32 v103, s[2:3], v69, v69, v191
	v_rcp_f32_e32 v105, v103
	s_nop 0
	v_fma_f32 v107, -v103, v105, 1.0
	v_fmac_f32_e32 v105, v107, v105
	v_div_scale_f32 v107, vcc, v191, v69, v191
	v_mul_f32_e32 v109, v107, v105
	v_fma_f32 v125, -v103, v109, v107
	v_fmac_f32_e32 v109, v125, v105
	v_fma_f32 v103, -v103, v109, v107
	v_div_fmas_f32 v103, v103, v105, v109
	v_div_fixup_f32 v65, v103, v69, v191
	v_div_scale_f32 v69, s[2:3], v68, v68, v190
	v_rcp_f32_e32 v103, v69
	v_pk_fma_f32 v[34:35], v[34:35], v[124:125], v[188:189] op_sel_hi:[1,0,1]
	s_waitcnt vmcnt(5)
	v_pk_fma_f32 v[36:37], v[36:37], v[124:125], v[194:195] op_sel_hi:[1,0,1]
	v_fma_f32 v105, -v69, v103, 1.0
	v_fmac_f32_e32 v103, v105, v103
	v_div_scale_f32 v105, vcc, v190, v68, v190
	v_mul_f32_e32 v107, v105, v103
	v_fma_f32 v109, -v69, v107, v105
	v_fmac_f32_e32 v107, v109, v103
	v_fma_f32 v69, -v69, v107, v105
	v_div_fmas_f32 v69, v69, v103, v107
	v_div_fixup_f32 v64, v69, v68, v190
	v_pk_mul_f32 v[64:65], v[32:33], v[64:65]
	v_cmp_nlt_f32_e32 vcc, s34, v192
	v_pk_fma_f32 v[32:33], v[64:65], v[64:65], v[126:127]
	v_mul_f32_e32 v68, v65, v65
	v_pk_add_f32 v[32:33], v[68:69], v[32:33] op_sel_hi:[0,1]
	v_mul_f32_e32 v68, 0xbfb8aa3b, v192
	v_fma_f32 v69, v192, s43, -v68
	v_rndne_f32_e32 v103, v68
	v_fmac_f32_e32 v69, 0xb2a5705f, v192
	v_sub_f32_e32 v68, v68, v103
	v_add_f32_e32 v68, v68, v69
	v_exp_f32_e32 v68, v68
	v_cvt_i32_f32_e32 v69, v103
	v_ldexp_f32 v68, v68, v69
	v_mul_f32_e32 v69, 0xbfb8aa3b, v193
	v_fma_f32 v103, v193, s43, -v69
	v_rndne_f32_e32 v105, v69
	v_fmac_f32_e32 v103, 0xb2a5705f, v193
	v_sub_f32_e32 v69, v69, v105
	v_add_f32_e32 v69, v69, v103
	v_exp_f32_e32 v69, v69
	v_cvt_i32_f32_e32 v103, v105
	v_cndmask_b32_e32 v68, 0, v68, vcc
	v_cmp_ngt_f32_e32 vcc, s35, v192
	v_ldexp_f32 v69, v69, v103
	s_nop 0
	v_cndmask_b32_e32 v68, v179, v68, vcc
	v_cmp_nlt_f32_e32 vcc, s34, v193
	s_nop 1
	v_cndmask_b32_e32 v69, 0, v69, vcc
	v_cmp_ngt_f32_e32 vcc, s35, v193
	s_nop 1
	v_cndmask_b32_e32 v69, v179, v69, vcc
	v_pk_add_f32 v[68:69], v[68:69], 1.0 op_sel_hi:[1,0]
	s_nop 0
	v_div_scale_f32 v70, s[2:3], v69, v69, v193
	v_rcp_f32_e32 v71, v70
	s_nop 0
	v_fma_f32 v103, -v70, v71, 1.0
	v_fmac_f32_e32 v71, v103, v71
	v_div_scale_f32 v103, vcc, v193, v69, v193
	v_mul_f32_e32 v105, v103, v71
	v_fma_f32 v107, -v70, v105, v103
	v_fmac_f32_e32 v105, v107, v71
	v_fma_f32 v70, -v70, v105, v103
	v_div_fmas_f32 v70, v70, v71, v105
	v_div_fixup_f32 v67, v70, v69, v193
	v_div_scale_f32 v69, s[2:3], v68, v68, v192
	v_rcp_f32_e32 v70, v69
	s_nop 0
	v_fma_f32 v71, -v69, v70, 1.0
	v_fmac_f32_e32 v70, v71, v70
	v_div_scale_f32 v71, vcc, v192, v68, v192
	v_mul_f32_e32 v103, v71, v70
	v_fma_f32 v105, -v69, v103, v71
	v_fmac_f32_e32 v103, v105, v70
	v_fma_f32 v69, -v69, v103, v71
	v_div_fmas_f32 v69, v69, v70, v103
	v_div_fixup_f32 v66, v69, v68, v192
	v_pk_mul_f32 v[66:67], v[34:35], v[66:67]
	s_waitcnt vmcnt(4)
	v_cmp_nlt_f32_e32 vcc, s34, v198
	v_pk_fma_f32 v[32:33], v[66:67], v[66:67], v[32:33]
	v_mul_f32_e32 v34, v67, v67
	v_pk_add_f32 v[32:33], v[34:35], v[32:33] op_sel_hi:[0,1]
	v_mul_f32_e32 v34, 0xbfb8aa3b, v198
	v_fma_f32 v35, v198, s43, -v34
	v_rndne_f32_e32 v68, v34
	v_fmac_f32_e32 v35, 0xb2a5705f, v198
	v_sub_f32_e32 v34, v34, v68
	v_add_f32_e32 v34, v34, v35
	v_exp_f32_e32 v34, v34
	v_cvt_i32_f32_e32 v35, v68
	v_ldexp_f32 v34, v34, v35
	v_mul_f32_e32 v35, 0xbfb8aa3b, v199
	v_fma_f32 v68, v199, s43, -v35
	v_rndne_f32_e32 v69, v35
	v_fmac_f32_e32 v68, 0xb2a5705f, v199
	v_sub_f32_e32 v35, v35, v69
	v_add_f32_e32 v35, v35, v68
	v_exp_f32_e32 v35, v35
	v_cvt_i32_f32_e32 v68, v69
	v_cndmask_b32_e32 v34, 0, v34, vcc
	v_cmp_ngt_f32_e32 vcc, s35, v198
	v_ldexp_f32 v35, v35, v68
	s_nop 0
	v_cndmask_b32_e32 v34, v179, v34, vcc
	v_cmp_nlt_f32_e32 vcc, s34, v199
	s_nop 1
	v_cndmask_b32_e32 v35, 0, v35, vcc
	v_cmp_ngt_f32_e32 vcc, s35, v199
	s_nop 1
	v_cndmask_b32_e32 v35, v179, v35, vcc
	v_pk_add_f32 v[34:35], v[34:35], 1.0 op_sel_hi:[1,0]
	s_nop 0
	v_div_scale_f32 v60, s[2:3], v35, v35, v199
	v_rcp_f32_e32 v61, v60
	s_nop 0
	v_fma_f32 v68, -v60, v61, 1.0
	v_fmac_f32_e32 v61, v68, v61
	v_div_scale_f32 v68, vcc, v199, v35, v199
	v_mul_f32_e32 v69, v68, v61
	v_fma_f32 v70, -v60, v69, v68
	v_fmac_f32_e32 v69, v70, v61
	v_fma_f32 v60, -v60, v69, v68
	v_div_fmas_f32 v60, v60, v61, v69
	v_div_fixup_f32 v35, v60, v35, v199
	v_div_scale_f32 v57, s[2:3], v34, v34, v198
	v_rcp_f32_e32 v60, v57
	s_nop 0
	v_fma_f32 v61, -v57, v60, 1.0
	v_fmac_f32_e32 v60, v61, v60
	v_div_scale_f32 v61, vcc, v198, v34, v198
	v_mul_f32_e32 v68, v61, v60
	v_fma_f32 v69, -v57, v68, v61
	v_fmac_f32_e32 v68, v69, v60
	v_fma_f32 v57, -v57, v68, v61
	v_div_fmas_f32 v57, v57, v60, v68
	v_div_fixup_f32 v34, v57, v34, v198
	v_pk_mul_f32 v[56:57], v[36:37], v[34:35]
	v_cmp_nlt_f32_e32 vcc, s34, v200
	v_pk_fma_f32 v[32:33], v[56:57], v[56:57], v[32:33]
	v_mul_f32_e32 v34, v57, v57
	v_pk_add_f32 v[32:33], v[34:35], v[32:33] op_sel_hi:[0,1]
	v_mul_f32_e32 v34, 0xbfb8aa3b, v200
	v_fma_f32 v35, v200, s43, -v34
	v_rndne_f32_e32 v36, v34
	v_fmac_f32_e32 v35, 0xb2a5705f, v200
	v_sub_f32_e32 v34, v34, v36
	v_add_f32_e32 v34, v34, v35
	v_exp_f32_e32 v34, v34
	v_cvt_i32_f32_e32 v35, v36
	v_ldexp_f32 v34, v34, v35
	v_mul_f32_e32 v35, 0xbfb8aa3b, v201
	v_fma_f32 v36, v201, s43, -v35
	v_rndne_f32_e32 v37, v35
	v_fmac_f32_e32 v36, 0xb2a5705f, v201
	v_sub_f32_e32 v35, v35, v37
	v_add_f32_e32 v35, v35, v36
	v_exp_f32_e32 v35, v35
	v_cvt_i32_f32_e32 v36, v37
	v_cndmask_b32_e32 v34, 0, v34, vcc
	v_cmp_ngt_f32_e32 vcc, s35, v200
	v_ldexp_f32 v35, v35, v36
	s_nop 0
	v_cndmask_b32_e32 v34, v179, v34, vcc
	v_cmp_nlt_f32_e32 vcc, s34, v201
	v_pk_fma_f32 v[36:37], v[38:39], v[124:125], v[196:197] op_sel_hi:[1,0,1]
	s_nop 0
	v_cndmask_b32_e32 v35, 0, v35, vcc
	v_cmp_ngt_f32_e32 vcc, s35, v201
	s_nop 1
	v_cndmask_b32_e32 v35, v179, v35, vcc
	v_pk_add_f32 v[34:35], v[34:35], 1.0 op_sel_hi:[1,0]
	s_nop 0
	v_div_scale_f32 v38, s[2:3], v35, v35, v201
	v_rcp_f32_e32 v39, v38
	s_nop 0
	v_fma_f32 v60, -v38, v39, 1.0
	v_fmac_f32_e32 v39, v60, v39
	v_div_scale_f32 v60, vcc, v201, v35, v201
	v_mul_f32_e32 v61, v60, v39
	v_fma_f32 v62, -v38, v61, v60
	v_fmac_f32_e32 v61, v62, v39
	v_fma_f32 v38, -v38, v61, v60
	v_div_fmas_f32 v38, v38, v39, v61
	v_div_fixup_f32 v35, v38, v35, v201
	v_div_scale_f32 v38, s[2:3], v34, v34, v200
	v_rcp_f32_e32 v39, v38
	s_nop 0
	v_fma_f32 v59, -v38, v39, 1.0
	v_fmac_f32_e32 v39, v59, v39
	v_div_scale_f32 v59, vcc, v200, v34, v200
	v_mul_f32_e32 v60, v59, v39
	v_fma_f32 v61, -v38, v60, v59
	v_fmac_f32_e32 v60, v61, v39
	v_fma_f32 v38, -v38, v60, v59
	v_div_fmas_f32 v38, v38, v39, v60
	v_div_fixup_f32 v34, v38, v34, v200
	v_pk_mul_f32 v[58:59], v[36:37], v[34:35]
	s_waitcnt vmcnt(2)
	v_cmp_nlt_f32_e32 vcc, s34, v206
	v_pk_fma_f32 v[32:33], v[58:59], v[58:59], v[32:33]
	v_mul_f32_e32 v34, v59, v59
	v_pk_add_f32 v[32:33], v[34:35], v[32:33] op_sel_hi:[0,1]
	v_mul_f32_e32 v34, 0xbfb8aa3b, v206
	v_fma_f32 v35, v206, s43, -v34
	v_rndne_f32_e32 v36, v34
	v_fmac_f32_e32 v35, 0xb2a5705f, v206
	v_sub_f32_e32 v34, v34, v36
	v_add_f32_e32 v34, v34, v35
	v_exp_f32_e32 v34, v34
	v_cvt_i32_f32_e32 v35, v36
	v_ldexp_f32 v34, v34, v35
	v_mul_f32_e32 v35, 0xbfb8aa3b, v207
	v_fma_f32 v36, v207, s43, -v35
	v_rndne_f32_e32 v37, v35
	v_fmac_f32_e32 v36, 0xb2a5705f, v207
	v_sub_f32_e32 v35, v35, v37
	v_add_f32_e32 v35, v35, v36
	v_exp_f32_e32 v35, v35
	v_cvt_i32_f32_e32 v36, v37
	v_cndmask_b32_e32 v34, 0, v34, vcc
	v_cmp_ngt_f32_e32 vcc, s35, v206
	v_ldexp_f32 v35, v35, v36
	s_nop 0
	v_cndmask_b32_e32 v34, v179, v34, vcc
	v_cmp_nlt_f32_e32 vcc, s34, v207
	v_pk_fma_f32 v[36:37], v[40:41], v[124:125], v[202:203] op_sel_hi:[1,0,1]
	s_nop 0
	v_cndmask_b32_e32 v35, 0, v35, vcc
	v_cmp_ngt_f32_e32 vcc, s35, v207
	s_nop 1
	v_cndmask_b32_e32 v35, v179, v35, vcc
	v_pk_add_f32 v[34:35], v[34:35], 1.0 op_sel_hi:[1,0]
	s_nop 0
	v_div_scale_f32 v38, s[2:3], v35, v35, v207
	v_rcp_f32_e32 v39, v38
	s_nop 0
	v_fma_f32 v40, -v38, v39, 1.0
	v_fmac_f32_e32 v39, v40, v39
	v_div_scale_f32 v40, vcc, v207, v35, v207
	v_mul_f32_e32 v41, v40, v39
	v_fma_f32 v52, -v38, v41, v40
	v_fmac_f32_e32 v41, v52, v39
	v_fma_f32 v38, -v38, v41, v40
	v_div_fmas_f32 v38, v38, v39, v41
	v_div_fixup_f32 v35, v38, v35, v207
	v_div_scale_f32 v38, s[2:3], v34, v34, v206
	v_rcp_f32_e32 v39, v38
	s_nop 0
	v_fma_f32 v40, -v38, v39, 1.0
	v_fmac_f32_e32 v39, v40, v39
	v_div_scale_f32 v40, vcc, v206, v34, v206
	v_mul_f32_e32 v41, v40, v39
	v_fma_f32 v49, -v38, v41, v40
	v_fmac_f32_e32 v41, v49, v39
	v_fma_f32 v38, -v38, v41, v40
	v_div_fmas_f32 v38, v38, v39, v41
	v_div_fixup_f32 v34, v38, v34, v206
	v_pk_mul_f32 v[48:49], v[36:37], v[34:35]
	v_cmp_nlt_f32_e32 vcc, s34, v208
	v_pk_fma_f32 v[32:33], v[48:49], v[48:49], v[32:33]
	v_mul_f32_e32 v34, v49, v49
	v_pk_add_f32 v[32:33], v[34:35], v[32:33] op_sel_hi:[0,1]
	v_mul_f32_e32 v34, 0xbfb8aa3b, v208
	v_fma_f32 v35, v208, s43, -v34
	v_rndne_f32_e32 v36, v34
	v_fmac_f32_e32 v35, 0xb2a5705f, v208
	v_sub_f32_e32 v34, v34, v36
	v_add_f32_e32 v34, v34, v35
	v_exp_f32_e32 v34, v34
	v_cvt_i32_f32_e32 v35, v36
	v_ldexp_f32 v34, v34, v35
	v_mul_f32_e32 v35, 0xbfb8aa3b, v209
	v_fma_f32 v36, v209, s43, -v35
	v_rndne_f32_e32 v37, v35
	v_fmac_f32_e32 v36, 0xb2a5705f, v209
	v_sub_f32_e32 v35, v35, v37
	v_add_f32_e32 v35, v35, v36
	v_exp_f32_e32 v35, v35
	v_cvt_i32_f32_e32 v36, v37
	v_cndmask_b32_e32 v34, 0, v34, vcc
	v_cmp_ngt_f32_e32 vcc, s35, v208
	v_ldexp_f32 v35, v35, v36
	s_nop 0
	v_cndmask_b32_e32 v34, v179, v34, vcc
	v_cmp_nlt_f32_e32 vcc, s34, v209
	v_pk_fma_f32 v[36:37], v[42:43], v[124:125], v[204:205] op_sel_hi:[1,0,1]
	s_nop 0
	v_cndmask_b32_e32 v35, 0, v35, vcc
	v_cmp_ngt_f32_e32 vcc, s35, v209
	s_nop 1
	v_cndmask_b32_e32 v35, v179, v35, vcc
	v_pk_add_f32 v[34:35], v[34:35], 1.0 op_sel_hi:[1,0]
	s_nop 0
	v_div_scale_f32 v38, s[2:3], v35, v35, v209
	v_rcp_f32_e32 v39, v38
	s_nop 0
	v_fma_f32 v40, -v38, v39, 1.0
	v_fmac_f32_e32 v39, v40, v39
	v_div_scale_f32 v40, vcc, v209, v35, v209
	v_mul_f32_e32 v41, v40, v39
	v_fma_f32 v42, -v38, v41, v40
	v_fmac_f32_e32 v41, v42, v39
	v_fma_f32 v38, -v38, v41, v40
	v_div_fmas_f32 v38, v38, v39, v41
	v_div_fixup_f32 v35, v38, v35, v209
	v_div_scale_f32 v38, s[2:3], v34, v34, v208
	v_rcp_f32_e32 v39, v38
	s_nop 0
	v_fma_f32 v40, -v38, v39, 1.0
	v_fmac_f32_e32 v39, v40, v39
	v_div_scale_f32 v40, vcc, v208, v34, v208
	v_mul_f32_e32 v41, v40, v39
	v_fma_f32 v42, -v38, v41, v40
	v_fmac_f32_e32 v41, v42, v39
	v_fma_f32 v38, -v38, v41, v40
	v_div_fmas_f32 v38, v38, v39, v41
	v_div_fixup_f32 v34, v38, v34, v208
	v_pk_mul_f32 v[52:53], v[36:37], v[34:35]
	s_waitcnt vmcnt(0)
	v_cmp_nlt_f32_e32 vcc, s34, v214
	v_pk_fma_f32 v[32:33], v[52:53], v[52:53], v[32:33]
	v_mul_f32_e32 v34, v53, v53
	v_pk_add_f32 v[32:33], v[34:35], v[32:33] op_sel_hi:[0,1]
	v_mul_f32_e32 v34, 0xbfb8aa3b, v214
	v_fma_f32 v35, v214, s43, -v34
	v_rndne_f32_e32 v36, v34
	v_fmac_f32_e32 v35, 0xb2a5705f, v214
	v_sub_f32_e32 v34, v34, v36
	v_add_f32_e32 v34, v34, v35
	v_exp_f32_e32 v34, v34
	v_cvt_i32_f32_e32 v35, v36
	v_ldexp_f32 v34, v34, v35
	v_mul_f32_e32 v35, 0xbfb8aa3b, v215
	v_fma_f32 v36, v215, s43, -v35
	v_rndne_f32_e32 v37, v35
	v_fmac_f32_e32 v36, 0xb2a5705f, v215
	v_sub_f32_e32 v35, v35, v37
	v_add_f32_e32 v35, v35, v36
	v_exp_f32_e32 v35, v35
	v_cvt_i32_f32_e32 v36, v37
	v_cndmask_b32_e32 v34, 0, v34, vcc
	v_cmp_ngt_f32_e32 vcc, s35, v214
	v_ldexp_f32 v35, v35, v36
	s_nop 0
	v_cndmask_b32_e32 v34, v179, v34, vcc
	v_cmp_nlt_f32_e32 vcc, s34, v215
	v_pk_fma_f32 v[36:37], v[44:45], v[124:125], v[210:211] op_sel_hi:[1,0,1]
	s_nop 0
	v_cndmask_b32_e32 v35, 0, v35, vcc
	v_cmp_ngt_f32_e32 vcc, s35, v215
	s_nop 1
	v_cndmask_b32_e32 v35, v179, v35, vcc
	v_pk_add_f32 v[34:35], v[34:35], 1.0 op_sel_hi:[1,0]
	s_nop 0
	v_div_scale_f32 v38, s[2:3], v35, v35, v215
	v_rcp_f32_e32 v39, v38
	s_nop 0
	v_fma_f32 v40, -v38, v39, 1.0
	v_fmac_f32_e32 v39, v40, v39
	v_div_scale_f32 v40, vcc, v215, v35, v215
	v_mul_f32_e32 v41, v40, v39
	v_fma_f32 v42, -v38, v41, v40
	v_fmac_f32_e32 v41, v42, v39
	v_fma_f32 v38, -v38, v41, v40
	v_div_fmas_f32 v38, v38, v39, v41
	v_div_fixup_f32 v35, v38, v35, v215
	v_div_scale_f32 v38, s[2:3], v34, v34, v214
	v_rcp_f32_e32 v39, v38
	s_nop 0
	v_fma_f32 v40, -v38, v39, 1.0
	v_fmac_f32_e32 v39, v40, v39
	v_div_scale_f32 v40, vcc, v214, v34, v214
	v_mul_f32_e32 v41, v40, v39
	v_fma_f32 v42, -v38, v41, v40
	v_fmac_f32_e32 v41, v42, v39
	v_fma_f32 v38, -v38, v41, v40
	v_div_fmas_f32 v38, v38, v39, v41
	v_div_fixup_f32 v34, v38, v34, v214
	v_pk_mul_f32 v[60:61], v[36:37], v[34:35]
	v_cmp_nlt_f32_e32 vcc, s34, v216
	v_pk_fma_f32 v[32:33], v[60:61], v[60:61], v[32:33]
	v_mul_f32_e32 v34, v61, v61
	v_pk_add_f32 v[32:33], v[34:35], v[32:33] op_sel_hi:[0,1]
	v_mul_f32_e32 v34, 0xbfb8aa3b, v216
	v_fma_f32 v35, v216, s43, -v34
	v_rndne_f32_e32 v36, v34
	v_fmac_f32_e32 v35, 0xb2a5705f, v216
	v_sub_f32_e32 v34, v34, v36
	v_add_f32_e32 v34, v34, v35
	v_exp_f32_e32 v34, v34
	v_cvt_i32_f32_e32 v35, v36
	v_ldexp_f32 v34, v34, v35
	v_mul_f32_e32 v35, 0xbfb8aa3b, v217
	v_fma_f32 v36, v217, s43, -v35
	v_rndne_f32_e32 v37, v35
	v_fmac_f32_e32 v36, 0xb2a5705f, v217
	v_sub_f32_e32 v35, v35, v37
	v_add_f32_e32 v35, v35, v36
	v_exp_f32_e32 v35, v35
	v_cvt_i32_f32_e32 v36, v37
	v_cndmask_b32_e32 v34, 0, v34, vcc
	v_cmp_ngt_f32_e32 vcc, s35, v216
	v_ldexp_f32 v35, v35, v36
	s_nop 0
	v_cndmask_b32_e32 v34, v179, v34, vcc
	v_cmp_nlt_f32_e32 vcc, s34, v217
	v_pk_fma_f32 v[36:37], v[46:47], v[124:125], v[212:213] op_sel_hi:[1,0,1]
	s_nop 0
	v_cndmask_b32_e32 v35, 0, v35, vcc
	v_cmp_ngt_f32_e32 vcc, s35, v217
	s_nop 1
	v_cndmask_b32_e32 v35, v179, v35, vcc
	v_pk_add_f32 v[34:35], v[34:35], 1.0 op_sel_hi:[1,0]
	s_nop 0
	v_div_scale_f32 v38, s[2:3], v35, v35, v217
	v_rcp_f32_e32 v39, v38
	s_nop 0
	v_fma_f32 v40, -v38, v39, 1.0
	v_fmac_f32_e32 v39, v40, v39
	v_div_scale_f32 v40, vcc, v217, v35, v217
	v_mul_f32_e32 v41, v40, v39
	v_fma_f32 v42, -v38, v41, v40
	v_fmac_f32_e32 v41, v42, v39
	v_fma_f32 v38, -v38, v41, v40
	v_div_fmas_f32 v38, v38, v39, v41
	v_div_fixup_f32 v35, v38, v35, v217
	v_div_scale_f32 v38, s[2:3], v34, v34, v216
	v_rcp_f32_e32 v39, v38
	s_nop 0
	v_fma_f32 v40, -v38, v39, 1.0
	v_fmac_f32_e32 v39, v40, v39
	v_div_scale_f32 v40, vcc, v216, v34, v216
	v_mul_f32_e32 v41, v40, v39
	v_fma_f32 v42, -v38, v41, v40
	v_fmac_f32_e32 v41, v42, v39
	v_fma_f32 v38, -v38, v41, v40
	v_div_fmas_f32 v38, v38, v39, v41
	v_div_fixup_f32 v34, v38, v34, v216
	v_pk_mul_f32 v[78:79], v[36:37], v[34:35]
	s_nop 0
	v_pk_fma_f32 v[32:33], v[78:79], v[78:79], v[32:33]
	v_mul_f32_e32 v34, v79, v79
	v_pk_add_f32 v[32:33], v[34:35], v[32:33] op_sel_hi:[0,1]
	v_mov_b32_e32 v33, v32
	s_nop 1
	v_permlane32_swap_b32_e32 v32, v33
	s_and_saveexec_b64 s[14:15], s[48:49]
	v_add_f32_e32 v32, v32, v33
	ds_write_b32 v97, v32
	s_or_b64 exec, exec, s[14:15]
	v_mov_b32_e32 v33, s5
	v_or_b32_e32 v32, s4, v92
	v_lshlrev_b64 v[34:35], 5, v[32:33]
	v_lshl_add_u64 v[34:35], s[8:9], 0, v[34:35]
	global_load_dword v143, v[34:35], off
	v_mad_u64_u32 v[132:133], s[2:3], v32, s42, v[98:99]
	v_lshlrev_b64 v[50:51], 11, v[32:33]
	s_mul_i32 s2, s5, 0x2800
	v_lshl_add_u64 v[130:131], v[94:95], 0, v[50:51]
	v_add_u32_e32 v133, s2, v133
	global_load_dwordx4 v[70:73], v[130:131], off
	global_load_dwordx4 v[74:77], v[132:133], off
	global_load_dwordx4 v[134:137], v[130:131], off offset:32
	global_load_dwordx4 v[138:141], v[132:133], off offset:32
	global_load_dwordx4 v[44:47], v[130:131], off offset:64
	global_load_dwordx4 v[40:43], v[132:133], off offset:64
	global_load_dwordx4 v[36:39], v[130:131], off offset:96
	global_load_dwordx4 v[32:35], v[132:133], off offset:96
	s_waitcnt vmcnt(8)
	v_exp_f32_e32 v126, v143
	s_waitcnt vmcnt(7)
	v_pk_fma_f32 v[16:17], v[16:17], v[126:127], v[70:71] op_sel_hi:[1,0,1]
	v_pk_fma_f32 v[18:19], v[18:19], v[126:127], v[72:73] op_sel_hi:[1,0,1]
	s_waitcnt vmcnt(6)
	v_mul_f32_e32 v54, 0xbfb8aa3b, v74
	v_fma_f32 v55, v74, s43, -v54
	v_rndne_f32_e32 v62, v54
	v_fmac_f32_e32 v55, 0xb2a5705f, v74
	v_sub_f32_e32 v54, v54, v62
	v_add_f32_e32 v54, v54, v55
	v_exp_f32_e32 v54, v54
	v_cvt_i32_f32_e32 v55, v62
	v_cmp_nlt_f32_e32 vcc, s34, v74
	s_waitcnt vmcnt(5)
	v_pk_fma_f32 v[20:21], v[20:21], v[126:127], v[134:135] op_sel_hi:[1,0,1]
	v_ldexp_f32 v54, v54, v55
	v_mul_f32_e32 v55, 0xbfb8aa3b, v75
	v_fma_f32 v62, v75, s43, -v55
	v_rndne_f32_e32 v63, v55
	v_fmac_f32_e32 v62, 0xb2a5705f, v75
	v_sub_f32_e32 v55, v55, v63
	v_add_f32_e32 v55, v55, v62
	v_exp_f32_e32 v55, v55
	v_cvt_i32_f32_e32 v62, v63
	v_cndmask_b32_e32 v54, 0, v54, vcc
	v_cmp_ngt_f32_e32 vcc, s35, v74
	v_ldexp_f32 v55, v55, v62
	s_nop 0
	v_cndmask_b32_e32 v54, v179, v54, vcc
	v_cmp_nlt_f32_e32 vcc, s34, v75
	s_nop 1
	v_cndmask_b32_e32 v55, 0, v55, vcc
	v_cmp_ngt_f32_e32 vcc, s35, v75
	s_nop 1
	v_cndmask_b32_e32 v55, v179, v55, vcc
	v_pk_add_f32 v[54:55], v[54:55], 1.0 op_sel_hi:[1,0]
	s_nop 0
	v_div_scale_f32 v62, s[2:3], v55, v55, v75
	v_rcp_f32_e32 v63, v62
	s_nop 0
	v_fma_f32 v68, -v62, v63, 1.0
	v_fmac_f32_e32 v63, v68, v63
	v_div_scale_f32 v68, vcc, v75, v55, v75
	v_mul_f32_e32 v69, v68, v63
	v_fma_f32 v70, -v62, v69, v68
	v_fmac_f32_e32 v69, v70, v63
	v_fma_f32 v62, -v62, v69, v68
	v_div_fmas_f32 v62, v62, v63, v69
	v_div_fixup_f32 v55, v62, v55, v75
	v_div_scale_f32 v62, s[2:3], v54, v54, v74
	v_rcp_f32_e32 v63, v62
	s_nop 0
	v_fma_f32 v68, -v62, v63, 1.0
	v_fmac_f32_e32 v63, v68, v63
	v_div_scale_f32 v68, vcc, v74, v54, v74
	v_mul_f32_e32 v69, v68, v63
	v_fma_f32 v70, -v62, v69, v68
	v_fmac_f32_e32 v69, v70, v63
	v_fma_f32 v62, -v62, v69, v68
	v_div_fmas_f32 v62, v62, v63, v69
	v_div_fixup_f32 v54, v62, v54, v74
	v_pk_mul_f32 v[70:71], v[16:17], v[54:55]
	v_mul_f32_e32 v54, 0xbfb8aa3b, v76
	v_fma_f32 v55, v76, s43, -v54
	v_rndne_f32_e32 v62, v54
	v_fmac_f32_e32 v55, 0xb2a5705f, v76
	v_sub_f32_e32 v54, v54, v62
	v_add_f32_e32 v54, v54, v55
	v_exp_f32_e32 v54, v54
	v_cvt_i32_f32_e32 v55, v62
	v_cmp_nlt_f32_e32 vcc, s34, v76
	v_mul_f32_e32 v16, v71, v71
	v_pk_fma_f32 v[16:17], v[70:71], v[70:71], v[16:17] op_sel_hi:[1,1,0]
	v_ldexp_f32 v54, v54, v55
	v_mul_f32_e32 v55, 0xbfb8aa3b, v77
	v_fma_f32 v62, v77, s43, -v55
	v_rndne_f32_e32 v63, v55
	v_fmac_f32_e32 v62, 0xb2a5705f, v77
	v_sub_f32_e32 v55, v55, v63
	v_add_f32_e32 v55, v55, v62
	v_exp_f32_e32 v55, v55
	v_cvt_i32_f32_e32 v62, v63
	v_cndmask_b32_e32 v54, 0, v54, vcc
	v_cmp_ngt_f32_e32 vcc, s35, v76
	v_ldexp_f32 v55, v55, v62
	s_nop 0
	v_cndmask_b32_e32 v54, v179, v54, vcc
	v_cmp_nlt_f32_e32 vcc, s34, v77
	s_nop 1
	v_cndmask_b32_e32 v55, 0, v55, vcc
	v_cmp_ngt_f32_e32 vcc, s35, v77
	s_nop 1
	v_cndmask_b32_e32 v55, v179, v55, vcc
	v_pk_add_f32 v[54:55], v[54:55], 1.0 op_sel_hi:[1,0]
	s_nop 0
	v_div_scale_f32 v62, s[2:3], v55, v55, v77
	v_rcp_f32_e32 v63, v62
	s_nop 0
	v_fma_f32 v68, -v62, v63, 1.0
	v_fmac_f32_e32 v63, v68, v63
	v_div_scale_f32 v68, vcc, v77, v55, v77
	v_mul_f32_e32 v69, v68, v63
	v_fma_f32 v72, -v62, v69, v68
	v_fmac_f32_e32 v69, v72, v63
	v_fma_f32 v62, -v62, v69, v68
	v_div_fmas_f32 v62, v62, v63, v69
	v_div_fixup_f32 v55, v62, v55, v77
	v_div_scale_f32 v62, s[2:3], v54, v54, v76
	v_rcp_f32_e32 v63, v62
	s_nop 0
	v_fma_f32 v68, -v62, v63, 1.0
	v_fmac_f32_e32 v63, v68, v63
	v_div_scale_f32 v68, vcc, v76, v54, v76
	v_mul_f32_e32 v69, v68, v63
	v_fma_f32 v72, -v62, v69, v68
	v_fmac_f32_e32 v69, v72, v63
	v_fma_f32 v62, -v62, v69, v68
	v_div_fmas_f32 v62, v62, v63, v69
	v_div_fixup_f32 v54, v62, v54, v76
	v_pk_mul_f32 v[74:75], v[18:19], v[54:55]
	s_waitcnt vmcnt(4)
	v_cmp_nlt_f32_e32 vcc, s34, v138
	v_pk_fma_f32 v[16:17], v[74:75], v[74:75], v[16:17]
	v_mul_f32_e32 v18, v75, v75
	v_pk_add_f32 v[16:17], v[18:19], v[16:17] op_sel_hi:[0,1]
	v_mul_f32_e32 v18, 0xbfb8aa3b, v138
	v_fma_f32 v19, v138, s43, -v18
	v_rndne_f32_e32 v54, v18
	v_fmac_f32_e32 v19, 0xb2a5705f, v138
	v_sub_f32_e32 v18, v18, v54
	v_add_f32_e32 v18, v18, v19
	v_exp_f32_e32 v18, v18
	v_cvt_i32_f32_e32 v19, v54
	v_ldexp_f32 v18, v18, v19
	v_mul_f32_e32 v19, 0xbfb8aa3b, v139
	v_fma_f32 v54, v139, s43, -v19
	v_rndne_f32_e32 v55, v19
	v_fmac_f32_e32 v54, 0xb2a5705f, v139
	v_sub_f32_e32 v19, v19, v55
	v_add_f32_e32 v19, v19, v54
	v_exp_f32_e32 v19, v19
	v_cvt_i32_f32_e32 v54, v55
	v_cndmask_b32_e32 v18, 0, v18, vcc
	v_cmp_ngt_f32_e32 vcc, s35, v138
	v_ldexp_f32 v19, v19, v54
	s_nop 0
	v_cndmask_b32_e32 v18, v179, v18, vcc
	v_cmp_nlt_f32_e32 vcc, s34, v139
	s_nop 1
	v_cndmask_b32_e32 v19, 0, v19, vcc
	v_cmp_ngt_f32_e32 vcc, s35, v139
	s_nop 1
	v_cndmask_b32_e32 v19, v179, v19, vcc
	v_pk_add_f32 v[18:19], v[18:19], 1.0 op_sel_hi:[1,0]
	s_nop 0
	v_div_scale_f32 v54, s[2:3], v19, v19, v139
	v_rcp_f32_e32 v55, v54
	s_nop 0
	v_fma_f32 v62, -v54, v55, 1.0
	v_fmac_f32_e32 v55, v62, v55
	v_div_scale_f32 v62, vcc, v139, v19, v139
	v_mul_f32_e32 v63, v62, v55
	v_fma_f32 v68, -v54, v63, v62
	v_fmac_f32_e32 v63, v68, v55
	v_fma_f32 v54, -v54, v63, v62
	v_div_fmas_f32 v54, v54, v55, v63
	v_div_fixup_f32 v19, v54, v19, v139
	v_div_scale_f32 v54, s[2:3], v18, v18, v138
	v_rcp_f32_e32 v55, v54
	s_nop 0
	v_fma_f32 v62, -v54, v55, 1.0
	v_fmac_f32_e32 v55, v62, v55
	v_div_scale_f32 v62, vcc, v138, v18, v138
	v_mul_f32_e32 v63, v62, v55
	v_fma_f32 v68, -v54, v63, v62
	v_fmac_f32_e32 v63, v68, v55
	v_fma_f32 v54, -v54, v63, v62
	v_div_fmas_f32 v54, v54, v55, v63
	v_div_fixup_f32 v18, v54, v18, v138
	v_pk_mul_f32 v[54:55], v[20:21], v[18:19]
	v_cmp_nlt_f32_e32 vcc, s34, v140
	v_pk_fma_f32 v[16:17], v[54:55], v[54:55], v[16:17]
	v_mul_f32_e32 v18, v55, v55
	v_pk_add_f32 v[16:17], v[18:19], v[16:17] op_sel_hi:[0,1]
	v_mul_f32_e32 v18, 0xbfb8aa3b, v140
	v_fma_f32 v19, v140, s43, -v18
	v_rndne_f32_e32 v20, v18
	v_fmac_f32_e32 v19, 0xb2a5705f, v140
	v_sub_f32_e32 v18, v18, v20
	v_add_f32_e32 v18, v18, v19
	v_exp_f32_e32 v18, v18
	v_cvt_i32_f32_e32 v19, v20
	v_ldexp_f32 v18, v18, v19
	v_mul_f32_e32 v19, 0xbfb8aa3b, v141
	v_fma_f32 v20, v141, s43, -v19
	v_rndne_f32_e32 v21, v19
	v_fmac_f32_e32 v20, 0xb2a5705f, v141
	v_sub_f32_e32 v19, v19, v21
	v_add_f32_e32 v19, v19, v20
	v_exp_f32_e32 v19, v19
	v_cvt_i32_f32_e32 v20, v21
	v_cndmask_b32_e32 v18, 0, v18, vcc
	v_cmp_ngt_f32_e32 vcc, s35, v140
	v_ldexp_f32 v19, v19, v20
	s_nop 0
	v_cndmask_b32_e32 v18, v179, v18, vcc
	v_cmp_nlt_f32_e32 vcc, s34, v141
	v_pk_fma_f32 v[20:21], v[22:23], v[126:127], v[136:137] op_sel_hi:[1,0,1]
	s_nop 0
	v_cndmask_b32_e32 v19, 0, v19, vcc
	v_cmp_ngt_f32_e32 vcc, s35, v141
	s_nop 1
	v_cndmask_b32_e32 v19, v179, v19, vcc
	v_pk_add_f32 v[18:19], v[18:19], 1.0 op_sel_hi:[1,0]
	s_nop 0
	v_div_scale_f32 v22, s[2:3], v19, v19, v141
	v_rcp_f32_e32 v23, v22
	s_nop 0
	v_fma_f32 v62, -v22, v23, 1.0
	v_fmac_f32_e32 v23, v62, v23
	v_div_scale_f32 v62, vcc, v141, v19, v141
	v_mul_f32_e32 v63, v62, v23
	v_fma_f32 v68, -v22, v63, v62
	v_fmac_f32_e32 v63, v68, v23
	v_fma_f32 v22, -v22, v63, v62
	v_div_fmas_f32 v22, v22, v23, v63
	v_div_fixup_f32 v19, v22, v19, v141
	v_div_scale_f32 v22, s[2:3], v18, v18, v140
	v_rcp_f32_e32 v23, v22
	s_nop 0
	v_fma_f32 v62, -v22, v23, 1.0
	v_fmac_f32_e32 v23, v62, v23
	v_div_scale_f32 v62, vcc, v140, v18, v140
	v_mul_f32_e32 v63, v62, v23
	v_fma_f32 v68, -v22, v63, v62
	v_fmac_f32_e32 v63, v68, v23
	v_fma_f32 v22, -v22, v63, v62
	v_div_fmas_f32 v22, v22, v23, v63
	v_div_fixup_f32 v18, v22, v18, v140
	v_pk_mul_f32 v[62:63], v[20:21], v[18:19]
	s_waitcnt vmcnt(2)
	v_cmp_nlt_f32_e32 vcc, s34, v40
	v_pk_fma_f32 v[16:17], v[62:63], v[62:63], v[16:17]
	v_mul_f32_e32 v18, v63, v63
	v_pk_add_f32 v[16:17], v[18:19], v[16:17] op_sel_hi:[0,1]
	v_mul_f32_e32 v18, 0xbfb8aa3b, v40
	v_fma_f32 v19, v40, s43, -v18
	v_rndne_f32_e32 v20, v18
	v_fmac_f32_e32 v19, 0xb2a5705f, v40
	v_sub_f32_e32 v18, v18, v20
	v_add_f32_e32 v18, v18, v19
	v_exp_f32_e32 v18, v18
	v_cvt_i32_f32_e32 v19, v20
	v_ldexp_f32 v18, v18, v19
	v_mul_f32_e32 v19, 0xbfb8aa3b, v41
	v_fma_f32 v20, v41, s43, -v19
	v_rndne_f32_e32 v21, v19
	v_fmac_f32_e32 v20, 0xb2a5705f, v41
	v_sub_f32_e32 v19, v19, v21
	v_add_f32_e32 v19, v19, v20
	v_exp_f32_e32 v19, v19
	v_cvt_i32_f32_e32 v20, v21
	v_cndmask_b32_e32 v18, 0, v18, vcc
	v_cmp_ngt_f32_e32 vcc, s35, v40
	v_ldexp_f32 v19, v19, v20
	s_nop 0
	v_cndmask_b32_e32 v18, v179, v18, vcc
	v_cmp_nlt_f32_e32 vcc, s34, v41
	v_pk_fma_f32 v[20:21], v[24:25], v[126:127], v[44:45] op_sel_hi:[1,0,1]
	s_nop 0
	v_cndmask_b32_e32 v19, 0, v19, vcc
	v_cmp_ngt_f32_e32 vcc, s35, v41
	s_nop 1
	v_cndmask_b32_e32 v19, v179, v19, vcc
	v_pk_add_f32 v[18:19], v[18:19], 1.0 op_sel_hi:[1,0]
	s_nop 0
	v_div_scale_f32 v22, s[2:3], v19, v19, v41
	v_rcp_f32_e32 v23, v22
	s_nop 0
	v_fma_f32 v24, -v22, v23, 1.0
	v_fmac_f32_e32 v23, v24, v23
	v_div_scale_f32 v24, vcc, v41, v19, v41
	v_mul_f32_e32 v25, v24, v23
	v_fma_f32 v44, -v22, v25, v24
	v_fmac_f32_e32 v25, v44, v23
	v_fma_f32 v22, -v22, v25, v24
	v_div_fmas_f32 v22, v22, v23, v25
	v_div_fixup_f32 v19, v22, v19, v41
	v_div_scale_f32 v22, s[2:3], v18, v18, v40
	v_rcp_f32_e32 v23, v22
	s_nop 0
	v_fma_f32 v24, -v22, v23, 1.0
	v_fmac_f32_e32 v23, v24, v23
	v_div_scale_f32 v24, vcc, v40, v18, v40
	v_mul_f32_e32 v25, v24, v23
	v_fma_f32 v41, -v22, v25, v24
	v_fmac_f32_e32 v25, v41, v23
	v_fma_f32 v22, -v22, v25, v24
	v_div_fmas_f32 v22, v22, v23, v25
	v_div_fixup_f32 v18, v22, v18, v40
	v_pk_mul_f32 v[68:69], v[20:21], v[18:19]
	v_cmp_nlt_f32_e32 vcc, s34, v42
	v_pk_fma_f32 v[16:17], v[68:69], v[68:69], v[16:17]
	v_mul_f32_e32 v18, v69, v69
	v_pk_add_f32 v[16:17], v[18:19], v[16:17] op_sel_hi:[0,1]
	v_mul_f32_e32 v18, 0xbfb8aa3b, v42
	v_fma_f32 v19, v42, s43, -v18
	v_rndne_f32_e32 v20, v18
	v_fmac_f32_e32 v19, 0xb2a5705f, v42
	v_sub_f32_e32 v18, v18, v20
	v_add_f32_e32 v18, v18, v19
	v_exp_f32_e32 v18, v18
	v_cvt_i32_f32_e32 v19, v20
	v_ldexp_f32 v18, v18, v19
	v_mul_f32_e32 v19, 0xbfb8aa3b, v43
	v_fma_f32 v20, v43, s43, -v19
	v_rndne_f32_e32 v21, v19
	v_fmac_f32_e32 v20, 0xb2a5705f, v43
	v_sub_f32_e32 v19, v19, v21
	v_add_f32_e32 v19, v19, v20
	v_exp_f32_e32 v19, v19
	v_cvt_i32_f32_e32 v20, v21
	v_cndmask_b32_e32 v18, 0, v18, vcc
	v_cmp_ngt_f32_e32 vcc, s35, v42
	v_ldexp_f32 v19, v19, v20
	s_nop 0
	v_cndmask_b32_e32 v18, v179, v18, vcc
	v_cmp_nlt_f32_e32 vcc, s34, v43
	v_pk_fma_f32 v[20:21], v[26:27], v[126:127], v[46:47] op_sel_hi:[1,0,1]
	s_nop 0
	v_cndmask_b32_e32 v19, 0, v19, vcc
	v_cmp_ngt_f32_e32 vcc, s35, v43
	s_nop 1
	v_cndmask_b32_e32 v19, v179, v19, vcc
	v_pk_add_f32 v[18:19], v[18:19], 1.0 op_sel_hi:[1,0]
	s_nop 0
	v_div_scale_f32 v22, s[2:3], v19, v19, v43
	v_rcp_f32_e32 v23, v22
	s_nop 0
	v_fma_f32 v24, -v22, v23, 1.0
	v_fmac_f32_e32 v23, v24, v23
	v_div_scale_f32 v24, vcc, v43, v19, v43
	v_mul_f32_e32 v25, v24, v23
	v_fma_f32 v26, -v22, v25, v24
	v_fmac_f32_e32 v25, v26, v23
	v_fma_f32 v22, -v22, v25, v24
	v_div_fmas_f32 v22, v22, v23, v25
	v_div_fixup_f32 v19, v22, v19, v43
	v_div_scale_f32 v22, s[2:3], v18, v18, v42
	v_rcp_f32_e32 v23, v22
	s_nop 0
	v_fma_f32 v24, -v22, v23, 1.0
	v_fmac_f32_e32 v23, v24, v23
	v_div_scale_f32 v24, vcc, v42, v18, v42
	v_mul_f32_e32 v25, v24, v23
	v_fma_f32 v26, -v22, v25, v24
	v_fmac_f32_e32 v25, v26, v23
	v_fma_f32 v22, -v22, v25, v24
	v_div_fmas_f32 v22, v22, v23, v25
	v_div_fixup_f32 v18, v22, v18, v42
	v_pk_mul_f32 v[72:73], v[20:21], v[18:19]
	s_waitcnt vmcnt(0)
	v_cmp_nlt_f32_e32 vcc, s34, v32
	v_pk_fma_f32 v[16:17], v[72:73], v[72:73], v[16:17]
	v_mul_f32_e32 v18, v73, v73
	v_pk_add_f32 v[16:17], v[18:19], v[16:17] op_sel_hi:[0,1]
	v_mul_f32_e32 v18, 0xbfb8aa3b, v32
	v_fma_f32 v19, v32, s43, -v18
	v_rndne_f32_e32 v20, v18
	v_fmac_f32_e32 v19, 0xb2a5705f, v32
	v_sub_f32_e32 v18, v18, v20
	v_add_f32_e32 v18, v18, v19
	v_exp_f32_e32 v18, v18
	v_cvt_i32_f32_e32 v19, v20
	v_ldexp_f32 v18, v18, v19
	v_mul_f32_e32 v19, 0xbfb8aa3b, v33
	v_fma_f32 v20, v33, s43, -v19
	v_rndne_f32_e32 v21, v19
	v_fmac_f32_e32 v20, 0xb2a5705f, v33
	v_sub_f32_e32 v19, v19, v21
	v_add_f32_e32 v19, v19, v20
	v_exp_f32_e32 v19, v19
	v_cvt_i32_f32_e32 v20, v21
	v_cndmask_b32_e32 v18, 0, v18, vcc
	v_cmp_ngt_f32_e32 vcc, s35, v32
	v_ldexp_f32 v19, v19, v20
	s_nop 0
	v_cndmask_b32_e32 v18, v179, v18, vcc
	v_cmp_nlt_f32_e32 vcc, s34, v33
	v_pk_fma_f32 v[20:21], v[28:29], v[126:127], v[36:37] op_sel_hi:[1,0,1]
	s_nop 0
	v_cndmask_b32_e32 v19, 0, v19, vcc
	v_cmp_ngt_f32_e32 vcc, s35, v33
	s_nop 1
	v_cndmask_b32_e32 v19, v179, v19, vcc
	v_pk_add_f32 v[18:19], v[18:19], 1.0 op_sel_hi:[1,0]
	s_nop 0
	v_div_scale_f32 v22, s[2:3], v19, v19, v33
	v_rcp_f32_e32 v23, v22
	s_nop 0
	v_fma_f32 v24, -v22, v23, 1.0
	v_fmac_f32_e32 v23, v24, v23
	v_div_scale_f32 v24, vcc, v33, v19, v33
	v_mul_f32_e32 v25, v24, v23
	v_fma_f32 v26, -v22, v25, v24
	v_fmac_f32_e32 v25, v26, v23
	v_fma_f32 v22, -v22, v25, v24
	v_div_fmas_f32 v22, v22, v23, v25
	v_div_fixup_f32 v19, v22, v19, v33
	v_div_scale_f32 v22, s[2:3], v18, v18, v32
	v_rcp_f32_e32 v23, v22
	s_nop 0
	v_fma_f32 v24, -v22, v23, 1.0
	v_fmac_f32_e32 v23, v24, v23
	v_div_scale_f32 v24, vcc, v32, v18, v32
	v_mul_f32_e32 v25, v24, v23
	v_fma_f32 v26, -v22, v25, v24
	v_fmac_f32_e32 v25, v26, v23
	v_fma_f32 v22, -v22, v25, v24
	v_div_fmas_f32 v22, v22, v23, v25
	v_div_fixup_f32 v18, v22, v18, v32
	v_pk_mul_f32 v[76:77], v[20:21], v[18:19]
	v_cmp_nlt_f32_e32 vcc, s34, v34
	v_pk_fma_f32 v[16:17], v[76:77], v[76:77], v[16:17]
	v_mul_f32_e32 v18, v77, v77
	v_pk_add_f32 v[16:17], v[18:19], v[16:17] op_sel_hi:[0,1]
	v_mul_f32_e32 v18, 0xbfb8aa3b, v34
	v_fma_f32 v19, v34, s43, -v18
	v_rndne_f32_e32 v20, v18
	v_fmac_f32_e32 v19, 0xb2a5705f, v34
	v_sub_f32_e32 v18, v18, v20
	v_add_f32_e32 v18, v18, v19
	v_exp_f32_e32 v18, v18
	v_cvt_i32_f32_e32 v19, v20
	v_ldexp_f32 v18, v18, v19
	v_mul_f32_e32 v19, 0xbfb8aa3b, v35
	v_fma_f32 v20, v35, s43, -v19
	v_rndne_f32_e32 v21, v19
	v_fmac_f32_e32 v20, 0xb2a5705f, v35
	v_sub_f32_e32 v19, v19, v21
	v_add_f32_e32 v19, v19, v20
	v_exp_f32_e32 v19, v19
	v_cvt_i32_f32_e32 v20, v21
	v_cndmask_b32_e32 v18, 0, v18, vcc
	v_cmp_ngt_f32_e32 vcc, s35, v34
	v_ldexp_f32 v19, v19, v20
	s_nop 0
	v_cndmask_b32_e32 v18, v179, v18, vcc
	v_cmp_nlt_f32_e32 vcc, s34, v35
	v_pk_fma_f32 v[20:21], v[30:31], v[126:127], v[38:39] op_sel_hi:[1,0,1]
	s_nop 0
	v_cndmask_b32_e32 v19, 0, v19, vcc
	v_cmp_ngt_f32_e32 vcc, s35, v35
	s_nop 1
	v_cndmask_b32_e32 v19, v179, v19, vcc
	v_pk_add_f32 v[18:19], v[18:19], 1.0 op_sel_hi:[1,0]
	s_nop 0
	v_div_scale_f32 v22, s[2:3], v19, v19, v35
	v_rcp_f32_e32 v23, v22
	s_nop 0
	v_fma_f32 v24, -v22, v23, 1.0
	v_fmac_f32_e32 v23, v24, v23
	v_div_scale_f32 v24, vcc, v35, v19, v35
	v_mul_f32_e32 v25, v24, v23
	v_fma_f32 v26, -v22, v25, v24
	v_fmac_f32_e32 v25, v26, v23
	v_fma_f32 v22, -v22, v25, v24
	v_div_fmas_f32 v22, v22, v23, v25
	v_div_fixup_f32 v19, v22, v19, v35
	v_div_scale_f32 v22, s[2:3], v18, v18, v34
	v_rcp_f32_e32 v23, v22
	s_nop 0
	v_fma_f32 v24, -v22, v23, 1.0
	v_fmac_f32_e32 v23, v24, v23
	v_div_scale_f32 v24, vcc, v34, v18, v34
	v_mul_f32_e32 v25, v24, v23
	v_fma_f32 v26, -v22, v25, v24
	v_fmac_f32_e32 v25, v26, v23
	v_fma_f32 v22, -v22, v25, v24
	v_div_fmas_f32 v22, v22, v23, v25
	v_div_fixup_f32 v18, v22, v18, v34
	v_pk_mul_f32 v[124:125], v[20:21], v[18:19]
	s_nop 0
	v_pk_fma_f32 v[16:17], v[124:125], v[124:125], v[16:17]
	v_mul_f32_e32 v18, v125, v125
	v_pk_add_f32 v[128:129], v[18:19], v[16:17] op_sel_hi:[0,1]
	global_load_dwordx4 v[36:39], v[130:131], off offset:128
	global_load_dwordx4 v[32:35], v[132:133], off offset:128
	global_load_dwordx4 v[28:31], v[130:131], off offset:160
	global_load_dwordx4 v[24:27], v[132:133], off offset:160
	global_load_dwordx4 v[20:23], v[130:131], off offset:192
	global_load_dwordx4 v[16:19], v[132:133], off offset:192
	global_load_dwordx4 v[44:47], v[130:131], off offset:224
	global_load_dwordx4 v[40:43], v[132:133], off offset:224
	s_waitcnt vmcnt(7)
	v_pk_fma_f32 v[0:1], v[0:1], v[126:127], v[36:37] op_sel_hi:[1,0,1]
	s_waitcnt vmcnt(6)
	v_mul_f32_e32 v103, 0xbfb8aa3b, v32
	v_fma_f32 v105, v32, s43, -v103
	v_rndne_f32_e32 v107, v103
	v_fmac_f32_e32 v105, 0xb2a5705f, v32
	v_sub_f32_e32 v103, v103, v107
	v_add_f32_e32 v103, v103, v105
	v_exp_f32_e32 v103, v103
	v_cvt_i32_f32_e32 v105, v107
	v_cmp_nlt_f32_e32 vcc, s34, v32
	v_ldexp_f32 v103, v103, v105
	s_nop 0
	v_cndmask_b32_e32 v103, 0, v103, vcc
	v_cmp_ngt_f32_e32 vcc, s35, v32
	s_nop 1
	v_cndmask_b32_e32 v130, v179, v103, vcc
	v_mul_f32_e32 v103, 0xbfb8aa3b, v33
	v_fma_f32 v105, v33, s43, -v103
	v_rndne_f32_e32 v107, v103
	v_fmac_f32_e32 v105, 0xb2a5705f, v33
	v_sub_f32_e32 v103, v103, v107
	v_add_f32_e32 v103, v103, v105
	v_exp_f32_e32 v103, v103
	v_cvt_i32_f32_e32 v105, v107
	v_cmp_nlt_f32_e32 vcc, s34, v33
	v_ldexp_f32 v103, v103, v105
	s_nop 0
	v_cndmask_b32_e32 v103, 0, v103, vcc
	v_cmp_ngt_f32_e32 vcc, s35, v33
	s_nop 1
	v_cndmask_b32_e32 v131, v179, v103, vcc
	v_pk_add_f32 v[36:37], v[130:131], 1.0 op_sel_hi:[1,0]
	s_nop 0
	v_div_scale_f32 v103, s[2:3], v37, v37, v33
	v_rcp_f32_e32 v105, v103
	s_nop 0
	v_fma_f32 v107, -v103, v105, 1.0
	v_fmac_f32_e32 v105, v107, v105
	v_div_scale_f32 v107, vcc, v33, v37, v33
	v_mul_f32_e32 v109, v107, v105
	v_fma_f32 v127, -v103, v109, v107
	v_fmac_f32_e32 v109, v127, v105
	v_fma_f32 v103, -v103, v109, v107
	v_div_fmas_f32 v103, v103, v105, v109
	v_div_fixup_f32 v33, v103, v37, v33
	v_div_scale_f32 v37, s[2:3], v36, v36, v32
	v_rcp_f32_e32 v103, v37
	v_pk_fma_f32 v[2:3], v[2:3], v[126:127], v[38:39] op_sel_hi:[1,0,1]
	s_waitcnt vmcnt(5)
	v_pk_fma_f32 v[4:5], v[4:5], v[126:127], v[28:29] op_sel_hi:[1,0,1]
	v_pk_fma_f32 v[6:7], v[6:7], v[126:127], v[30:31] op_sel_hi:[1,0,1]
	v_fma_f32 v105, -v37, v103, 1.0
	v_fmac_f32_e32 v103, v105, v103
	v_div_scale_f32 v105, vcc, v32, v36, v32
	v_mul_f32_e32 v107, v105, v103
	v_fma_f32 v109, -v37, v107, v105
	v_fmac_f32_e32 v107, v109, v103
	v_fma_f32 v37, -v37, v107, v105
	v_div_fmas_f32 v37, v37, v103, v107
	v_div_fixup_f32 v32, v37, v36, v32
	v_pk_mul_f32 v[0:1], v[0:1], v[32:33]
	v_cmp_nlt_f32_e32 vcc, s34, v34
	v_pk_fma_f32 v[32:33], v[0:1], v[0:1], v[128:129]
	v_mul_f32_e32 v36, v1, v1
	v_pk_add_f32 v[32:33], v[36:37], v[32:33] op_sel_hi:[0,1]
	v_mul_f32_e32 v36, 0xbfb8aa3b, v34
	v_fma_f32 v37, v34, s43, -v36
	v_rndne_f32_e32 v103, v36
	v_fmac_f32_e32 v37, 0xb2a5705f, v34
	v_sub_f32_e32 v36, v36, v103
	v_add_f32_e32 v36, v36, v37
	v_exp_f32_e32 v36, v36
	v_cvt_i32_f32_e32 v37, v103
	s_waitcnt vmcnt(3)
	v_pk_fma_f32 v[8:9], v[8:9], v[126:127], v[20:21] op_sel_hi:[1,0,1]
	v_pk_fma_f32 v[10:11], v[10:11], v[126:127], v[22:23] op_sel_hi:[1,0,1]
	s_waitcnt vmcnt(1)
	v_pk_fma_f32 v[12:13], v[12:13], v[126:127], v[44:45] op_sel_hi:[1,0,1]
	v_ldexp_f32 v36, v36, v37
	v_mul_f32_e32 v37, 0xbfb8aa3b, v35
	v_fma_f32 v103, v35, s43, -v37
	v_rndne_f32_e32 v105, v37
	v_fmac_f32_e32 v103, 0xb2a5705f, v35
	v_sub_f32_e32 v37, v37, v105
	v_add_f32_e32 v37, v37, v103
	v_exp_f32_e32 v37, v37
	v_cvt_i32_f32_e32 v103, v105
	v_cndmask_b32_e32 v36, 0, v36, vcc
	v_cmp_ngt_f32_e32 vcc, s35, v34
	v_pk_fma_f32 v[14:15], v[14:15], v[126:127], v[46:47] op_sel_hi:[1,0,1]
	v_ldexp_f32 v37, v37, v103
	v_cndmask_b32_e32 v36, v179, v36, vcc
	v_cmp_nlt_f32_e32 vcc, s34, v35
	s_nop 1
	v_cndmask_b32_e32 v37, 0, v37, vcc
	v_cmp_ngt_f32_e32 vcc, s35, v35
	s_nop 1
	v_cndmask_b32_e32 v37, v179, v37, vcc
	v_pk_add_f32 v[36:37], v[36:37], 1.0 op_sel_hi:[1,0]
	s_nop 0
	v_div_scale_f32 v38, s[2:3], v37, v37, v35
	v_rcp_f32_e32 v39, v38
	s_nop 0
	v_fma_f32 v103, -v38, v39, 1.0
	v_fmac_f32_e32 v39, v103, v39
	v_div_scale_f32 v103, vcc, v35, v37, v35
	v_mul_f32_e32 v105, v103, v39
	v_fma_f32 v107, -v38, v105, v103
	v_fmac_f32_e32 v105, v107, v39
	v_fma_f32 v38, -v38, v105, v103
	v_div_fmas_f32 v38, v38, v39, v105
	v_div_fixup_f32 v35, v38, v37, v35
	v_div_scale_f32 v37, s[2:3], v36, v36, v34
	v_rcp_f32_e32 v38, v37
	s_nop 0
	v_fma_f32 v39, -v37, v38, 1.0
	v_fmac_f32_e32 v38, v39, v38
	v_div_scale_f32 v39, vcc, v34, v36, v34
	v_mul_f32_e32 v103, v39, v38
	v_fma_f32 v105, -v37, v103, v39
	v_fmac_f32_e32 v103, v105, v38
	v_fma_f32 v37, -v37, v103, v39
	v_div_fmas_f32 v37, v37, v38, v103
	v_div_fixup_f32 v34, v37, v36, v34
	v_pk_mul_f32 v[2:3], v[2:3], v[34:35]
	v_cmp_nlt_f32_e32 vcc, s34, v24
	v_pk_fma_f32 v[32:33], v[2:3], v[2:3], v[32:33]
	v_mul_f32_e32 v34, v3, v3
	v_pk_add_f32 v[32:33], v[34:35], v[32:33] op_sel_hi:[0,1]
	v_mul_f32_e32 v34, 0xbfb8aa3b, v24
	v_fma_f32 v35, v24, s43, -v34
	v_rndne_f32_e32 v36, v34
	v_fmac_f32_e32 v35, 0xb2a5705f, v24
	v_sub_f32_e32 v34, v34, v36
	v_add_f32_e32 v34, v34, v35
	v_exp_f32_e32 v34, v34
	v_cvt_i32_f32_e32 v35, v36
	v_ldexp_f32 v34, v34, v35
	v_mul_f32_e32 v35, 0xbfb8aa3b, v25
	v_fma_f32 v36, v25, s43, -v35
	v_rndne_f32_e32 v37, v35
	v_fmac_f32_e32 v36, 0xb2a5705f, v25
	v_sub_f32_e32 v35, v35, v37
	v_add_f32_e32 v35, v35, v36
	v_exp_f32_e32 v35, v35
	v_cvt_i32_f32_e32 v36, v37
	v_cndmask_b32_e32 v34, 0, v34, vcc
	v_cmp_ngt_f32_e32 vcc, s35, v24
	v_ldexp_f32 v35, v35, v36
	s_nop 0
	v_cndmask_b32_e32 v34, v179, v34, vcc
	v_cmp_nlt_f32_e32 vcc, s34, v25
	s_nop 1
	v_cndmask_b32_e32 v35, 0, v35, vcc
	v_cmp_ngt_f32_e32 vcc, s35, v25
	s_nop 1
	v_cndmask_b32_e32 v35, v179, v35, vcc
	v_pk_add_f32 v[28:29], v[34:35], 1.0 op_sel_hi:[1,0]
	s_nop 0
	v_div_scale_f32 v34, s[2:3], v29, v29, v25
	v_rcp_f32_e32 v35, v34
	s_nop 0
	v_fma_f32 v36, -v34, v35, 1.0
	v_fmac_f32_e32 v35, v36, v35
	v_div_scale_f32 v36, vcc, v25, v29, v25
	v_mul_f32_e32 v37, v36, v35
	v_fma_f32 v38, -v34, v37, v36
	v_fmac_f32_e32 v37, v38, v35
	v_fma_f32 v34, -v34, v37, v36
	v_div_fmas_f32 v34, v34, v35, v37
	v_div_fixup_f32 v25, v34, v29, v25
	v_div_scale_f32 v29, s[2:3], v28, v28, v24
	v_rcp_f32_e32 v34, v29
	s_nop 0
	v_fma_f32 v35, -v29, v34, 1.0
	v_fmac_f32_e32 v34, v35, v34
	v_div_scale_f32 v35, vcc, v24, v28, v24
	v_mul_f32_e32 v36, v35, v34
	v_fma_f32 v37, -v29, v36, v35
	v_fmac_f32_e32 v36, v37, v34
	v_fma_f32 v29, -v29, v36, v35
	v_div_fmas_f32 v29, v29, v34, v36
	v_div_fixup_f32 v24, v29, v28, v24
	v_pk_mul_f32 v[4:5], v[4:5], v[24:25]
	v_cmp_nlt_f32_e32 vcc, s34, v26
	v_pk_fma_f32 v[24:25], v[4:5], v[4:5], v[32:33]
	v_mul_f32_e32 v28, v5, v5
	v_pk_add_f32 v[24:25], v[28:29], v[24:25] op_sel_hi:[0,1]
	v_mul_f32_e32 v28, 0xbfb8aa3b, v26
	v_fma_f32 v29, v26, s43, -v28
	v_rndne_f32_e32 v32, v28
	v_fmac_f32_e32 v29, 0xb2a5705f, v26
	v_sub_f32_e32 v28, v28, v32
	v_add_f32_e32 v28, v28, v29
	v_exp_f32_e32 v28, v28
	v_cvt_i32_f32_e32 v29, v32
	v_ldexp_f32 v28, v28, v29
	v_mul_f32_e32 v29, 0xbfb8aa3b, v27
	v_fma_f32 v32, v27, s43, -v29
	v_rndne_f32_e32 v33, v29
	v_fmac_f32_e32 v32, 0xb2a5705f, v27
	v_sub_f32_e32 v29, v29, v33
	v_add_f32_e32 v29, v29, v32
	v_exp_f32_e32 v29, v29
	v_cvt_i32_f32_e32 v32, v33
	v_cndmask_b32_e32 v28, 0, v28, vcc
	v_cmp_ngt_f32_e32 vcc, s35, v26
	v_ldexp_f32 v29, v29, v32
	s_nop 0
	v_cndmask_b32_e32 v28, v179, v28, vcc
	v_cmp_nlt_f32_e32 vcc, s34, v27
	s_nop 1
	v_cndmask_b32_e32 v29, 0, v29, vcc
	v_cmp_ngt_f32_e32 vcc, s35, v27
	s_nop 1
	v_cndmask_b32_e32 v29, v179, v29, vcc
	v_pk_add_f32 v[28:29], v[28:29], 1.0 op_sel_hi:[1,0]
	s_nop 0
	v_div_scale_f32 v30, s[2:3], v29, v29, v27
	v_rcp_f32_e32 v31, v30
	s_nop 0
	v_fma_f32 v32, -v30, v31, 1.0
	v_fmac_f32_e32 v31, v32, v31
	v_div_scale_f32 v32, vcc, v27, v29, v27
	v_mul_f32_e32 v33, v32, v31
	v_fma_f32 v34, -v30, v33, v32
	v_fmac_f32_e32 v33, v34, v31
	v_fma_f32 v30, -v30, v33, v32
	v_div_fmas_f32 v30, v30, v31, v33
	v_div_fixup_f32 v27, v30, v29, v27
	v_div_scale_f32 v29, s[2:3], v28, v28, v26
	v_rcp_f32_e32 v30, v29
	s_nop 0
	v_fma_f32 v31, -v29, v30, 1.0
	v_fmac_f32_e32 v30, v31, v30
	v_div_scale_f32 v31, vcc, v26, v28, v26
	v_mul_f32_e32 v32, v31, v30
	v_fma_f32 v33, -v29, v32, v31
	v_fmac_f32_e32 v32, v33, v30
	v_fma_f32 v29, -v29, v32, v31
	v_div_fmas_f32 v29, v29, v30, v32
	v_div_fixup_f32 v26, v29, v28, v26
	v_pk_mul_f32 v[6:7], v[6:7], v[26:27]
	v_cmp_nlt_f32_e32 vcc, s34, v16
	v_pk_fma_f32 v[24:25], v[6:7], v[6:7], v[24:25]
	v_mul_f32_e32 v26, v7, v7
	v_pk_add_f32 v[24:25], v[26:27], v[24:25] op_sel_hi:[0,1]
	v_mul_f32_e32 v26, 0xbfb8aa3b, v16
	v_fma_f32 v27, v16, s43, -v26
	v_rndne_f32_e32 v28, v26
	v_fmac_f32_e32 v27, 0xb2a5705f, v16
	v_sub_f32_e32 v26, v26, v28
	v_add_f32_e32 v26, v26, v27
	v_exp_f32_e32 v26, v26
	v_cvt_i32_f32_e32 v27, v28
	v_ldexp_f32 v26, v26, v27
	v_mul_f32_e32 v27, 0xbfb8aa3b, v17
	v_fma_f32 v28, v17, s43, -v27
	v_rndne_f32_e32 v29, v27
	v_fmac_f32_e32 v28, 0xb2a5705f, v17
	v_sub_f32_e32 v27, v27, v29
	v_add_f32_e32 v27, v27, v28
	v_exp_f32_e32 v27, v27
	v_cvt_i32_f32_e32 v28, v29
	v_cndmask_b32_e32 v26, 0, v26, vcc
	v_cmp_ngt_f32_e32 vcc, s35, v16
	v_ldexp_f32 v27, v27, v28
	s_nop 0
	v_cndmask_b32_e32 v26, v179, v26, vcc
	v_cmp_nlt_f32_e32 vcc, s34, v17
	s_nop 1
	v_cndmask_b32_e32 v27, 0, v27, vcc
	v_cmp_ngt_f32_e32 vcc, s35, v17
	s_nop 1
	v_cndmask_b32_e32 v27, v179, v27, vcc
	v_pk_add_f32 v[20:21], v[26:27], 1.0 op_sel_hi:[1,0]
	s_nop 0
	v_div_scale_f32 v26, s[2:3], v21, v21, v17
	v_rcp_f32_e32 v27, v26
	s_nop 0
	v_fma_f32 v28, -v26, v27, 1.0
	v_fmac_f32_e32 v27, v28, v27
	v_div_scale_f32 v28, vcc, v17, v21, v17
	v_mul_f32_e32 v29, v28, v27
	v_fma_f32 v30, -v26, v29, v28
	v_fmac_f32_e32 v29, v30, v27
	v_fma_f32 v26, -v26, v29, v28
	v_div_fmas_f32 v26, v26, v27, v29
	v_div_fixup_f32 v17, v26, v21, v17
	v_div_scale_f32 v21, s[2:3], v20, v20, v16
	v_rcp_f32_e32 v26, v21
	s_nop 0
	v_fma_f32 v27, -v21, v26, 1.0
	v_fmac_f32_e32 v26, v27, v26
	v_div_scale_f32 v27, vcc, v16, v20, v16
	v_mul_f32_e32 v28, v27, v26
	v_fma_f32 v29, -v21, v28, v27
	v_fmac_f32_e32 v28, v29, v26
	v_fma_f32 v21, -v21, v28, v27
	v_div_fmas_f32 v21, v21, v26, v28
	v_div_fixup_f32 v16, v21, v20, v16
	v_pk_mul_f32 v[8:9], v[8:9], v[16:17]
	v_cmp_nlt_f32_e32 vcc, s34, v18
	v_pk_fma_f32 v[16:17], v[8:9], v[8:9], v[24:25]
	v_mul_f32_e32 v20, v9, v9
	v_pk_add_f32 v[16:17], v[20:21], v[16:17] op_sel_hi:[0,1]
	v_mul_f32_e32 v20, 0xbfb8aa3b, v18
	v_fma_f32 v21, v18, s43, -v20
	v_rndne_f32_e32 v24, v20
	v_fmac_f32_e32 v21, 0xb2a5705f, v18
	v_sub_f32_e32 v20, v20, v24
	v_add_f32_e32 v20, v20, v21
	v_exp_f32_e32 v20, v20
	v_cvt_i32_f32_e32 v21, v24
	v_ldexp_f32 v20, v20, v21
	v_mul_f32_e32 v21, 0xbfb8aa3b, v19
	v_fma_f32 v24, v19, s43, -v21
	v_rndne_f32_e32 v25, v21
	v_fmac_f32_e32 v24, 0xb2a5705f, v19
	v_sub_f32_e32 v21, v21, v25
	v_add_f32_e32 v21, v21, v24
	v_exp_f32_e32 v21, v21
	v_cvt_i32_f32_e32 v24, v25
	v_cndmask_b32_e32 v20, 0, v20, vcc
	v_cmp_ngt_f32_e32 vcc, s35, v18
	v_ldexp_f32 v21, v21, v24
	s_nop 0
	v_cndmask_b32_e32 v20, v179, v20, vcc
	v_cmp_nlt_f32_e32 vcc, s34, v19
	s_nop 1
	v_cndmask_b32_e32 v21, 0, v21, vcc
	v_cmp_ngt_f32_e32 vcc, s35, v19
	s_nop 1
	v_cndmask_b32_e32 v21, v179, v21, vcc
	v_pk_add_f32 v[20:21], v[20:21], 1.0 op_sel_hi:[1,0]
	s_nop 0
	v_div_scale_f32 v22, s[2:3], v21, v21, v19
	v_rcp_f32_e32 v23, v22
	s_nop 0
	v_fma_f32 v24, -v22, v23, 1.0
	v_fmac_f32_e32 v23, v24, v23
	v_div_scale_f32 v24, vcc, v19, v21, v19
	v_mul_f32_e32 v25, v24, v23
	v_fma_f32 v26, -v22, v25, v24
	v_fmac_f32_e32 v25, v26, v23
	v_fma_f32 v22, -v22, v25, v24
	v_div_fmas_f32 v22, v22, v23, v25
	v_div_fixup_f32 v19, v22, v21, v19
	v_div_scale_f32 v21, s[2:3], v20, v20, v18
	v_rcp_f32_e32 v22, v21
	s_nop 0
	v_fma_f32 v23, -v21, v22, 1.0
	v_fmac_f32_e32 v22, v23, v22
	v_div_scale_f32 v23, vcc, v18, v20, v18
	v_mul_f32_e32 v24, v23, v22
	v_fma_f32 v25, -v21, v24, v23
	v_fmac_f32_e32 v24, v25, v22
	v_fma_f32 v21, -v21, v24, v23
	v_div_fmas_f32 v21, v21, v22, v24
	v_div_fixup_f32 v18, v21, v20, v18
	v_pk_mul_f32 v[10:11], v[10:11], v[18:19]
	s_waitcnt vmcnt(0)
	v_cmp_nlt_f32_e32 vcc, s34, v40
	v_pk_fma_f32 v[16:17], v[10:11], v[10:11], v[16:17]
	v_mul_f32_e32 v18, v11, v11
	v_pk_add_f32 v[16:17], v[18:19], v[16:17] op_sel_hi:[0,1]
	v_mul_f32_e32 v18, 0xbfb8aa3b, v40
	v_fma_f32 v19, v40, s43, -v18
	v_rndne_f32_e32 v20, v18
	v_fmac_f32_e32 v19, 0xb2a5705f, v40
	v_sub_f32_e32 v18, v18, v20
	v_add_f32_e32 v18, v18, v19
	v_exp_f32_e32 v18, v18
	v_cvt_i32_f32_e32 v19, v20
	v_ldexp_f32 v18, v18, v19
	v_mul_f32_e32 v19, 0xbfb8aa3b, v41
	v_fma_f32 v20, v41, s43, -v19
	v_rndne_f32_e32 v21, v19
	v_fmac_f32_e32 v20, 0xb2a5705f, v41
	v_sub_f32_e32 v19, v19, v21
	v_add_f32_e32 v19, v19, v20
	v_exp_f32_e32 v19, v19
	v_cvt_i32_f32_e32 v20, v21
	v_cndmask_b32_e32 v18, 0, v18, vcc
	v_cmp_ngt_f32_e32 vcc, s35, v40
	v_ldexp_f32 v19, v19, v20
	s_nop 0
	v_cndmask_b32_e32 v18, v179, v18, vcc
	v_cmp_nlt_f32_e32 vcc, s34, v41
	s_nop 1
	v_cndmask_b32_e32 v19, 0, v19, vcc
	v_cmp_ngt_f32_e32 vcc, s35, v41
	s_nop 1
	v_cndmask_b32_e32 v19, v179, v19, vcc
	v_pk_add_f32 v[18:19], v[18:19], 1.0 op_sel_hi:[1,0]
	s_nop 0
	v_div_scale_f32 v20, s[2:3], v19, v19, v41
	v_rcp_f32_e32 v21, v20
	s_nop 0
	v_fma_f32 v22, -v20, v21, 1.0
	v_fmac_f32_e32 v21, v22, v21
	v_div_scale_f32 v22, vcc, v41, v19, v41
	v_mul_f32_e32 v23, v22, v21
	v_fma_f32 v24, -v20, v23, v22
	v_fmac_f32_e32 v23, v24, v21
	v_fma_f32 v20, -v20, v23, v22
	v_div_fmas_f32 v20, v20, v21, v23
	v_div_fixup_f32 v19, v20, v19, v41
	v_div_scale_f32 v20, s[2:3], v18, v18, v40
	v_rcp_f32_e32 v21, v20
	s_nop 0
	v_fma_f32 v22, -v20, v21, 1.0
	v_fmac_f32_e32 v21, v22, v21
	v_div_scale_f32 v22, vcc, v40, v18, v40
	v_mul_f32_e32 v23, v22, v21
	v_fma_f32 v24, -v20, v23, v22
	v_fmac_f32_e32 v23, v24, v21
	v_fma_f32 v20, -v20, v23, v22
	v_div_fmas_f32 v20, v20, v21, v23
	v_div_fixup_f32 v18, v20, v18, v40
	v_pk_mul_f32 v[12:13], v[12:13], v[18:19]
	v_cmp_nlt_f32_e32 vcc, s34, v42
	v_pk_fma_f32 v[16:17], v[12:13], v[12:13], v[16:17]
	v_mul_f32_e32 v18, v13, v13
	v_pk_add_f32 v[16:17], v[18:19], v[16:17] op_sel_hi:[0,1]
	v_mul_f32_e32 v18, 0xbfb8aa3b, v42
	v_fma_f32 v19, v42, s43, -v18
	v_rndne_f32_e32 v20, v18
	v_fmac_f32_e32 v19, 0xb2a5705f, v42
	v_sub_f32_e32 v18, v18, v20
	v_add_f32_e32 v18, v18, v19
	v_exp_f32_e32 v18, v18
	v_cvt_i32_f32_e32 v19, v20
	v_ldexp_f32 v18, v18, v19
	v_mul_f32_e32 v19, 0xbfb8aa3b, v43
	v_fma_f32 v20, v43, s43, -v19
	v_rndne_f32_e32 v21, v19
	v_fmac_f32_e32 v20, 0xb2a5705f, v43
	v_sub_f32_e32 v19, v19, v21
	v_add_f32_e32 v19, v19, v20
	v_exp_f32_e32 v19, v19
	v_cvt_i32_f32_e32 v20, v21
	v_cndmask_b32_e32 v18, 0, v18, vcc
	v_cmp_ngt_f32_e32 vcc, s35, v42
	v_ldexp_f32 v19, v19, v20
	s_nop 0
	v_cndmask_b32_e32 v18, v179, v18, vcc
	v_cmp_nlt_f32_e32 vcc, s34, v43
	s_nop 1
	v_cndmask_b32_e32 v19, 0, v19, vcc
	v_cmp_ngt_f32_e32 vcc, s35, v43
	s_nop 1
	v_cndmask_b32_e32 v19, v179, v19, vcc
	v_pk_add_f32 v[18:19], v[18:19], 1.0 op_sel_hi:[1,0]
	s_nop 0
	v_div_scale_f32 v20, s[2:3], v19, v19, v43
	v_rcp_f32_e32 v21, v20
	s_nop 0
	v_fma_f32 v22, -v20, v21, 1.0
	v_fmac_f32_e32 v21, v22, v21
	v_div_scale_f32 v22, vcc, v43, v19, v43
	v_mul_f32_e32 v23, v22, v21
	v_fma_f32 v24, -v20, v23, v22
	v_fmac_f32_e32 v23, v24, v21
	v_fma_f32 v20, -v20, v23, v22
	v_div_fmas_f32 v20, v20, v21, v23
	v_div_fixup_f32 v19, v20, v19, v43
	v_div_scale_f32 v20, s[2:3], v18, v18, v42
	v_rcp_f32_e32 v21, v20
	s_nop 0
	v_fma_f32 v22, -v20, v21, 1.0
	v_fmac_f32_e32 v21, v22, v21
	v_div_scale_f32 v22, vcc, v42, v18, v42
	v_mul_f32_e32 v23, v22, v21
	v_fma_f32 v24, -v20, v23, v22
	v_fmac_f32_e32 v23, v24, v21
	v_fma_f32 v20, -v20, v23, v22
	v_div_fmas_f32 v20, v20, v21, v23
	v_div_fixup_f32 v18, v20, v18, v42
	v_pk_mul_f32 v[14:15], v[14:15], v[18:19]
	s_nop 0
	v_pk_fma_f32 v[16:17], v[14:15], v[14:15], v[16:17]
	v_mul_f32_e32 v18, v15, v15
	v_pk_add_f32 v[16:17], v[18:19], v[16:17] op_sel_hi:[0,1]
	v_mov_b32_e32 v17, v16
	s_nop 1
	v_permlane32_swap_b32_e32 v16, v17
	s_and_saveexec_b64 s[4:5], s[48:49]
	s_cbranch_execz .LBB0_1284
	v_add_f32_e32 v16, v16, v17
	ds_write_b32 v97, v16 offset:1024
	s_branch .LBB0_1284
